# residual epilogues: counted waits per row group instead of one full drain, lane sums by row swaps instead of LDS bpermute
# baseline (speedup 1.0000x reference)
; #define PG8_GAS __attribute__((address_space(1)))
; __device__ __forceinline__ unsigned pk2_(float lo, float hi) { f32x2c_t v = {lo, hi}; bf16x2c_t b = __builtin_convertvector(v, bf16x2c_t); return __builtin_bit_cast(unsigned, b); }
;     __device__ __forceinline__ void operator()(const f32x4 (&acc)[2][2][4][2], const Unit& u, int wr, int wc, int fr, int fq) const {
;         typedef unsigned u32x2v __attribute__((ext_vector_type(2)));
;         const int row0 = u.pm * BM + wr * 64 + fr, col0 = u.pn * BM + wc * 32 + 4 * fq;
;         u32x2v bsv[2][4][2][2];
; #pragma unroll
;         for (int ai = 0; ai < 2; ++ai)
; #pragma unroll
;             for (int m = 0; m < 4; ++m) { const size_t off = (size_t)(row0 + ai * HALF + m * 16) * 1024 + col0;
; #pragma unroll
;                 for (int bj = 0; bj < 2; ++bj)
; #pragma unroll
;                     for (int n = 0; n < 2; ++n) bsv[ai][m][bj][n] = *(const PG8_GAS u32x2v*)(hbase + off + bj * HALF + n * 16); }
; #pragma unroll
;         for (int ai = 0; ai < 2; ++ai)
; #pragma unroll
;             for (int m = 0; m < 4; ++m) {
;                 const int r = row0 + ai * HALF + m * 16; const size_t off = (size_t)r * 1024 + col0; float ss = 0.f;
; #pragma unroll
;                 for (int bj = 0; bj < 2; ++bj)
; #pragma unroll
;                     for (int n = 0; n < 2; ++n) {
;                         const u32x2v w0 = bsv[ai][m][bj][n]; f32x4 bs;
;                         bs[0] = __builtin_bit_cast(float, w0.x << 16); bs[1] = __builtin_bit_cast(float, w0.x & 0xffff0000u); bs[2] = __builtin_bit_cast(float, w0.y << 16); bs[3] = __builtin_bit_cast(float, w0.y & 0xffff0000u);
;                         const f32x4 v = bs + acc[ai][bj][m][n] * alpha;
;                         { u32x2v w; w.x = pk2_(v[0], v[1]); w.y = pk2_(v[2], v[3]); *(PG8_GAS u32x2v*)(hb + off + bj * HALF + n * 16) = w; }
;                         ss += (v[0] * v[0] + v[1] * v[1]) + (v[2] * v[2] + v[3] * v[3]);
;                     }
;                 ss += __shfl_xor(ss, 16); ss += __shfl_xor(ss, 32);
;                 if (fq == 0) ((PG8_GAS float*)parts)[(size_t)r * 16 + u.pn * 4 + wc] = ss;
;             }
.LBB0_771:
	s_lshl_b32 s34, s58, 8
	v_mov_b32_e32 v136, v252
	s_add_i32 s34, s34, s49
	v_and_b32_e32 v233, 64, v231
	v_and_or_b32 v220, v136, 15, s34
	s_lshl_b32 s34, s12, 8
	v_bfe_u32 v224, v136, 4, 2
	s_or_b32 s34, s34, s50
	v_lshl_or_b32 v138, v224, 2, s34
	v_ashrrev_i32_e32 v139, 31, v138
	v_lshlrev_b64 v[234:235], 1, v[138:139]
	v_ashrrev_i32_e32 v221, 31, v220
	v_lshl_add_u64 v[140:141], s[14:15], 0, v[234:235]
	v_lshlrev_b64 v[236:237], 11, v[220:221]
	v_lshl_add_u64 v[136:137], v[140:141], 0, v[236:237]
	global_load_dwordx2 v[238:239], v[136:137], off
	global_load_dwordx2 v[240:241], v[136:137], off offset:32
	global_load_dwordx2 v[242:243], v[136:137], off offset:256
	global_load_dwordx2 v[244:245], v[136:137], off offset:288
	v_or_b32_e32 v208, 16, v220
	v_ashrrev_i32_e32 v209, 31, v208
	v_or_b32_e32 v196, 32, v220
	v_lshlrev_b64 v[218:219], 11, v[208:209]
	v_ashrrev_i32_e32 v197, 31, v196
	v_or_b32_e32 v184, 48, v220
	v_lshl_add_u64 v[136:137], v[140:141], 0, v[218:219]
	v_lshlrev_b64 v[206:207], 11, v[196:197]
	v_ashrrev_i32_e32 v185, 31, v184
	v_add_u32_e32 v172, 0x80, v220
	global_load_dwordx2 v[222:223], v[136:137], off
	global_load_dwordx2 v[216:217], v[136:137], off offset:32
	global_load_dwordx2 v[214:215], v[136:137], off offset:256
	global_load_dwordx2 v[212:213], v[136:137], off offset:288
	v_lshl_add_u64 v[136:137], v[140:141], 0, v[206:207]
	v_lshlrev_b64 v[194:195], 11, v[184:185]
	v_ashrrev_i32_e32 v173, 31, v172
	v_add_u32_e32 v160, 0x90, v220
	global_load_dwordx2 v[210:211], v[136:137], off
	global_load_dwordx2 v[204:205], v[136:137], off offset:32
	global_load_dwordx2 v[202:203], v[136:137], off offset:256
	global_load_dwordx2 v[200:201], v[136:137], off offset:288
	v_lshl_add_u64 v[136:137], v[140:141], 0, v[194:195]
	v_lshlrev_b64 v[182:183], 11, v[172:173]
	v_ashrrev_i32_e32 v161, 31, v160
	v_add_u32_e32 v148, 0xa0, v220
	global_load_dwordx2 v[198:199], v[136:137], off
	global_load_dwordx2 v[192:193], v[136:137], off offset:32
	global_load_dwordx2 v[190:191], v[136:137], off offset:256
	global_load_dwordx2 v[188:189], v[136:137], off offset:288
	v_lshl_add_u64 v[136:137], v[140:141], 0, v[182:183]
	v_lshlrev_b64 v[170:171], 11, v[160:161]
	v_ashrrev_i32_e32 v149, 31, v148
	global_load_dwordx2 v[186:187], v[136:137], off
	global_load_dwordx2 v[180:181], v[136:137], off offset:32
	global_load_dwordx2 v[178:179], v[136:137], off offset:256
	global_load_dwordx2 v[176:177], v[136:137], off offset:288
	v_lshl_add_u64 v[136:137], v[140:141], 0, v[170:171]
	v_lshlrev_b64 v[158:159], 11, v[148:149]
	global_load_dwordx2 v[174:175], v[136:137], off
	global_load_dwordx2 v[168:169], v[136:137], off offset:32
	global_load_dwordx2 v[166:167], v[136:137], off offset:256
	global_load_dwordx2 v[164:165], v[136:137], off offset:288
	v_lshl_add_u64 v[136:137], v[140:141], 0, v[158:159]
	global_load_dwordx2 v[162:163], v[136:137], off
	global_load_dwordx2 v[156:157], v[136:137], off offset:32
	global_load_dwordx2 v[154:155], v[136:137], off offset:256
	global_load_dwordx2 v[152:153], v[136:137], off offset:288
	v_add_u32_e32 v136, 0xb0, v220
	v_ashrrev_i32_e32 v137, 31, v136
	v_lshlrev_b64 v[146:147], 11, v[136:137]
	v_lshl_add_u64 v[140:141], v[140:141], 0, v[146:147]
	global_load_dwordx2 v[150:151], v[140:141], off
	global_load_dwordx2 v[144:145], v[140:141], off offset:32
	global_load_dwordx2 v[142:143], v[140:141], off offset:256
	s_nop 0
	global_load_dwordx2 v[140:141], v[140:141], off offset:288
	v_xor_b32_e32 v232, 16, v231
	v_add_u32_e32 v233, 64, v233
	v_xor_b32_e32 v246, 32, v231
	v_cmp_lt_i32_e32 vcc, v232, v233
	v_lshl_add_u64 v[236:237], s[16:17], 0, v[236:237]
	s_lshl_b32 s34, s12, 2
	v_cndmask_b32_e32 v232, v231, v232, vcc
	v_cmp_lt_i32_e32 vcc, v246, v233
	v_lshlrev_b32_e32 v233, 2, v232
	v_lshl_add_u64 v[234:235], v[236:237], 0, v[234:235]
	v_cndmask_b32_e32 v246, v231, v246, vcc
	v_lshlrev_b32_e32 v232, 2, v246
	v_cmp_eq_u32_e32 vcc, 0, v224
	s_ashr_i32 s35, s34, 31
	s_waitcnt vmcnt(28)
	v_lshlrev_b32_e32 v246, 16, v238
	v_and_b32_e32 v247, 0xffff0000, v238
	v_lshlrev_b32_e32 v238, 16, v239
	v_and_b32_e32 v239, 0xffff0000, v239
	v_pk_fma_f32 v[124:125], v[124:125], 0.5, v[246:247] op_sel_hi:[1,0,1]
	v_pk_fma_f32 v[126:127], v[126:127], 0.5, v[238:239] op_sel_hi:[1,0,1]
	v_cvt_pk_bf16_f32 v238, v124, v125
	v_mul_f32_e32 v125, v125, v125
	v_fmac_f32_e32 v125, v124, v124
	v_mul_f32_e32 v124, v127, v127
	v_fmac_f32_e32 v124, v126, v126
	v_add_f32_e32 v224, v125, v124
	v_lshlrev_b32_e32 v124, 16, v240
	v_and_b32_e32 v125, 0xffff0000, v240
	v_cvt_pk_bf16_f32 v239, v126, v127
	v_lshlrev_b32_e32 v126, 16, v241
	v_and_b32_e32 v127, 0xffff0000, v241
	v_pk_fma_f32 v[120:121], v[120:121], 0.5, v[124:125] op_sel_hi:[1,0,1]
	v_pk_fma_f32 v[122:123], v[122:123], 0.5, v[126:127] op_sel_hi:[1,0,1]
	v_cvt_pk_bf16_f32 v124, v120, v121
	v_mul_f32_e32 v121, v121, v121
	v_fmac_f32_e32 v121, v120, v120
	v_mul_f32_e32 v120, v123, v123
	v_fmac_f32_e32 v120, v122, v122
	v_add_f32_e32 v120, v121, v120
	v_add_f32_e32 v125, v224, v120
	v_lshlrev_b32_e32 v120, 16, v242
	v_and_b32_e32 v121, 0xffff0000, v242
	v_lshlrev_b32_e32 v126, 16, v243
	v_and_b32_e32 v127, 0xffff0000, v243
	v_pk_fma_f32 v[118:119], v[118:119], 0.5, v[126:127] op_sel_hi:[1,0,1]
	v_pk_fma_f32 v[116:117], v[116:117], 0.5, v[120:121] op_sel_hi:[1,0,1]
	v_mul_f32_e32 v121, v119, v119
	v_mul_f32_e32 v120, v117, v117
	v_fmac_f32_e32 v120, v116, v116
	v_fmac_f32_e32 v121, v118, v118
	v_add_f32_e32 v120, v120, v121
	v_add_f32_e32 v125, v125, v120
	v_lshlrev_b32_e32 v120, 16, v244
	v_and_b32_e32 v121, 0xffff0000, v244
	v_lshlrev_b32_e32 v126, 16, v245
	v_and_b32_e32 v127, 0xffff0000, v245
	v_pk_fma_f32 v[114:115], v[114:115], 0.5, v[126:127] op_sel_hi:[1,0,1]
	v_pk_fma_f32 v[120:121], v[112:113], 0.5, v[120:121] op_sel_hi:[1,0,1]
	v_mul_f32_e32 v113, v115, v115
	v_mul_f32_e32 v112, v121, v121
	v_fmac_f32_e32 v112, v120, v120
	v_fmac_f32_e32 v113, v114, v114
	v_add_f32_e32 v112, v112, v113
	v_add_f32_e32 v112, v125, v112
	v_mov_b32_e32 v113, v112
	s_nop 1
	v_permlane16_swap_b32_e32 v112, v113
	v_cvt_pk_bf16_f32 v116, v116, v117
	v_cvt_pk_bf16_f32 v117, v118, v119
	v_cvt_pk_bf16_f32 v125, v122, v123
	global_store_dwordx2 v[234:235], v[116:117], off offset:256
	s_waitcnt lgkmcnt(0)
	v_add_f32_e32 v112, v112, v113
	v_mov_b32_e32 v113, v112
	s_nop 1
	v_permlane32_swap_b32_e32 v112, v113
	v_cvt_pk_bf16_f32 v116, v120, v121
	v_cvt_pk_bf16_f32 v117, v114, v115
	global_store_dwordx2 v[234:235], v[238:239], off
	global_store_dwordx2 v[234:235], v[124:125], off offset:32
	global_store_dwordx2 v[234:235], v[116:117], off offset:288
	s_and_saveexec_b64 s[36:37], vcc
	s_cbranch_execz .LBB0_773
	v_lshlrev_b64 v[114:115], 6, v[220:221]
	v_lshl_add_u64 v[114:115], s[18:19], 0, v[114:115]
	v_lshl_add_u64 v[114:115], s[34:35], 2, v[114:115]
	s_lshl_b32 s12, s48, 2
	v_lshl_add_u64 v[114:115], v[114:115], 0, s[12:13]
	s_waitcnt lgkmcnt(0)
	v_add_f32_e32 v112, v112, v113
	global_store_dword v[114:115], v112, off
; #define PG8_GAS __attribute__((address_space(1)))
; __device__ __forceinline__ unsigned pk2_(float lo, float hi) { f32x2c_t v = {lo, hi}; bf16x2c_t b = __builtin_convertvector(v, bf16x2c_t); return __builtin_bit_cast(unsigned, b); }
;     __device__ __forceinline__ void operator()(const f32x4 (&acc)[2][2][4][2], const Unit& u, int wr, int wc, int fr, int fq) const {
;     ...
;         for (int ai = 0; ai < 2; ++ai)
; #pragma unroll
;             for (int m = 0; m < 4; ++m) {
;                 const int r = row0 + ai * HALF + m * 16; const size_t off = (size_t)r * 1024 + col0; float ss = 0.f;
; #pragma unroll
;                 for (int bj = 0; bj < 2; ++bj)
; #pragma unroll
;                     for (int n = 0; n < 2; ++n) {
;                         const u32x2v w0 = bsv[ai][m][bj][n]; f32x4 bs;
;                         bs[0] = __builtin_bit_cast(float, w0.x << 16); bs[1] = __builtin_bit_cast(float, w0.x & 0xffff0000u); bs[2] = __builtin_bit_cast(float, w0.y << 16); bs[3] = __builtin_bit_cast(float, w0.y & 0xffff0000u);
;                         const f32x4 v = bs + acc[ai][bj][m][n] * alpha;
;                         { u32x2v w; w.x = pk2_(v[0], v[1]); w.y = pk2_(v[2], v[3]); *(PG8_GAS u32x2v*)(hb + off + bj * HALF + n * 16) = w; }
;                         ss += (v[0] * v[0] + v[1] * v[1]) + (v[2] * v[2] + v[3] * v[3]);
;                     }
;                 ss += __shfl_xor(ss, 16); ss += __shfl_xor(ss, 32);
;                 if (fq == 0) ((PG8_GAS float*)parts)[(size_t)r * 16 + u.pn * 4 + wc] = ss;
;             }
.LBB0_773:
	s_or_b64 exec, exec, s[36:37]
	s_waitcnt vmcnt(28)
	v_lshlrev_b32_e32 v112, 16, v222
	s_waitcnt lgkmcnt(0)
	v_and_b32_e32 v113, 0xffff0000, v222
	v_lshlrev_b32_e32 v114, 16, v223
	v_and_b32_e32 v115, 0xffff0000, v223
	v_pk_fma_f32 v[108:109], v[108:109], 0.5, v[112:113] op_sel_hi:[1,0,1]
	v_pk_fma_f32 v[110:111], v[110:111], 0.5, v[114:115] op_sel_hi:[1,0,1]
	v_cvt_pk_bf16_f32 v112, v108, v109
	v_mul_f32_e32 v109, v109, v109
	v_lshl_add_u64 v[114:115], s[16:17], 0, v[218:219]
	v_fmac_f32_e32 v109, v108, v108
	v_mul_f32_e32 v108, v111, v111
	v_cvt_pk_bf16_f32 v113, v110, v111
	v_lshl_add_u64 v[114:115], v[138:139], 1, v[114:115]
	v_fmac_f32_e32 v108, v110, v110
	global_store_dwordx2 v[114:115], v[112:113], off
	v_add_f32_e32 v112, v109, v108
	v_lshlrev_b32_e32 v108, 16, v216
	v_and_b32_e32 v109, 0xffff0000, v216
	v_lshlrev_b32_e32 v110, 16, v217
	v_and_b32_e32 v111, 0xffff0000, v217
	v_pk_fma_f32 v[104:105], v[104:105], 0.5, v[108:109] op_sel_hi:[1,0,1]
	v_pk_fma_f32 v[106:107], v[106:107], 0.5, v[110:111] op_sel_hi:[1,0,1]
	v_cvt_pk_bf16_f32 v108, v104, v105
	v_mul_f32_e32 v105, v105, v105
	v_fmac_f32_e32 v105, v104, v104
	v_mul_f32_e32 v104, v107, v107
	v_fmac_f32_e32 v104, v106, v106
	v_add_f32_e32 v104, v105, v104
	v_add_f32_e32 v109, v112, v104
	v_lshlrev_b32_e32 v104, 16, v214
	v_and_b32_e32 v105, 0xffff0000, v214
	v_lshlrev_b32_e32 v110, 16, v215
	v_and_b32_e32 v111, 0xffff0000, v215
	v_pk_fma_f32 v[102:103], v[102:103], 0.5, v[110:111] op_sel_hi:[1,0,1]
	v_pk_fma_f32 v[100:101], v[100:101], 0.5, v[104:105] op_sel_hi:[1,0,1]
	v_mul_f32_e32 v105, v103, v103
	v_mul_f32_e32 v104, v101, v101
	v_fmac_f32_e32 v104, v100, v100
	v_fmac_f32_e32 v105, v102, v102
	v_add_f32_e32 v104, v104, v105
	v_add_f32_e32 v109, v109, v104
	v_lshlrev_b32_e32 v104, 16, v212
	v_and_b32_e32 v105, 0xffff0000, v212
	v_lshlrev_b32_e32 v110, 16, v213
	v_and_b32_e32 v111, 0xffff0000, v213
	v_pk_fma_f32 v[98:99], v[98:99], 0.5, v[110:111] op_sel_hi:[1,0,1]
	v_pk_fma_f32 v[104:105], v[96:97], 0.5, v[104:105] op_sel_hi:[1,0,1]
	v_mul_f32_e32 v97, v99, v99
	v_mul_f32_e32 v96, v105, v105
	v_fmac_f32_e32 v96, v104, v104
	v_fmac_f32_e32 v97, v98, v98
	v_add_f32_e32 v96, v96, v97
	v_add_f32_e32 v96, v109, v96
	v_mov_b32_e32 v97, v96
	s_nop 1
	v_permlane16_swap_b32_e32 v96, v97
	v_cvt_pk_bf16_f32 v100, v100, v101
	v_cvt_pk_bf16_f32 v101, v102, v103
	v_cvt_pk_bf16_f32 v109, v106, v107
	global_store_dwordx2 v[114:115], v[100:101], off offset:256
	s_waitcnt lgkmcnt(0)
	v_add_f32_e32 v96, v96, v97
	v_mov_b32_e32 v97, v96
	s_nop 1
	v_permlane32_swap_b32_e32 v96, v97
	v_cvt_pk_bf16_f32 v100, v104, v105
	v_cvt_pk_bf16_f32 v101, v98, v99
	global_store_dwordx2 v[114:115], v[108:109], off offset:32
	global_store_dwordx2 v[114:115], v[100:101], off offset:288
	s_and_saveexec_b64 s[36:37], vcc
	s_cbranch_execz .LBB0_775
	v_lshlrev_b64 v[98:99], 6, v[208:209]
	v_lshl_add_u64 v[98:99], s[18:19], 0, v[98:99]
	v_lshl_add_u64 v[98:99], s[34:35], 2, v[98:99]
	s_lshl_b32 s12, s48, 2
	v_lshl_add_u64 v[98:99], v[98:99], 0, s[12:13]
	s_waitcnt lgkmcnt(0)
	v_add_f32_e32 v96, v96, v97
	global_store_dword v[98:99], v96, off
.LBB0_775:
	s_or_b64 exec, exec, s[36:37]
	s_waitcnt vmcnt(28)
	v_lshlrev_b32_e32 v96, 16, v210
	s_waitcnt lgkmcnt(0)
	v_and_b32_e32 v97, 0xffff0000, v210
	v_lshlrev_b32_e32 v98, 16, v211
	v_and_b32_e32 v99, 0xffff0000, v211
	v_pk_fma_f32 v[92:93], v[92:93], 0.5, v[96:97] op_sel_hi:[1,0,1]
	v_pk_fma_f32 v[94:95], v[94:95], 0.5, v[98:99] op_sel_hi:[1,0,1]
	v_cvt_pk_bf16_f32 v96, v92, v93
	v_mul_f32_e32 v93, v93, v93
	v_lshl_add_u64 v[98:99], s[16:17], 0, v[206:207]
	v_fmac_f32_e32 v93, v92, v92
	v_mul_f32_e32 v92, v95, v95
	v_cvt_pk_bf16_f32 v97, v94, v95
	v_lshl_add_u64 v[98:99], v[138:139], 1, v[98:99]
	v_fmac_f32_e32 v92, v94, v94
	global_store_dwordx2 v[98:99], v[96:97], off
	v_add_f32_e32 v96, v93, v92
	v_lshlrev_b32_e32 v92, 16, v204
	v_and_b32_e32 v93, 0xffff0000, v204
	v_lshlrev_b32_e32 v94, 16, v205
	v_and_b32_e32 v95, 0xffff0000, v205
	v_pk_fma_f32 v[88:89], v[88:89], 0.5, v[92:93] op_sel_hi:[1,0,1]
	v_pk_fma_f32 v[90:91], v[90:91], 0.5, v[94:95] op_sel_hi:[1,0,1]
	v_cvt_pk_bf16_f32 v92, v88, v89
	v_mul_f32_e32 v89, v89, v89
	v_fmac_f32_e32 v89, v88, v88
	v_mul_f32_e32 v88, v91, v91
	v_fmac_f32_e32 v88, v90, v90
	v_add_f32_e32 v88, v89, v88
	v_add_f32_e32 v93, v96, v88
	v_lshlrev_b32_e32 v88, 16, v202
	v_and_b32_e32 v89, 0xffff0000, v202
	v_lshlrev_b32_e32 v94, 16, v203
	v_and_b32_e32 v95, 0xffff0000, v203
	v_pk_fma_f32 v[86:87], v[86:87], 0.5, v[94:95] op_sel_hi:[1,0,1]
	v_pk_fma_f32 v[84:85], v[84:85], 0.5, v[88:89] op_sel_hi:[1,0,1]
	v_mul_f32_e32 v89, v87, v87
	v_mul_f32_e32 v88, v85, v85
	v_fmac_f32_e32 v88, v84, v84
	v_fmac_f32_e32 v89, v86, v86
	v_add_f32_e32 v88, v88, v89
	v_add_f32_e32 v93, v93, v88
	v_lshlrev_b32_e32 v88, 16, v200
	v_and_b32_e32 v89, 0xffff0000, v200
	v_lshlrev_b32_e32 v94, 16, v201
	v_and_b32_e32 v95, 0xffff0000, v201
	v_pk_fma_f32 v[82:83], v[82:83], 0.5, v[94:95] op_sel_hi:[1,0,1]
	v_pk_fma_f32 v[88:89], v[80:81], 0.5, v[88:89] op_sel_hi:[1,0,1]
	v_mul_f32_e32 v81, v83, v83
	v_mul_f32_e32 v80, v89, v89
	v_fmac_f32_e32 v80, v88, v88
	v_fmac_f32_e32 v81, v82, v82
	v_add_f32_e32 v80, v80, v81
	v_add_f32_e32 v80, v93, v80
	v_mov_b32_e32 v81, v80
	s_nop 1
	v_permlane16_swap_b32_e32 v80, v81
	v_cvt_pk_bf16_f32 v84, v84, v85
	v_cvt_pk_bf16_f32 v85, v86, v87
	v_cvt_pk_bf16_f32 v93, v90, v91
	global_store_dwordx2 v[98:99], v[84:85], off offset:256
	s_waitcnt lgkmcnt(0)
	v_add_f32_e32 v80, v80, v81
	v_mov_b32_e32 v81, v80
	s_nop 1
	v_permlane32_swap_b32_e32 v80, v81
	v_cvt_pk_bf16_f32 v84, v88, v89
	v_cvt_pk_bf16_f32 v85, v82, v83
	global_store_dwordx2 v[98:99], v[92:93], off offset:32
	global_store_dwordx2 v[98:99], v[84:85], off offset:288
	s_and_saveexec_b64 s[36:37], vcc
	s_cbranch_execz .LBB0_777
	v_lshlrev_b64 v[82:83], 6, v[196:197]
	v_lshl_add_u64 v[82:83], s[18:19], 0, v[82:83]
	v_lshl_add_u64 v[82:83], s[34:35], 2, v[82:83]
	s_lshl_b32 s12, s48, 2
	v_lshl_add_u64 v[82:83], v[82:83], 0, s[12:13]
	s_waitcnt lgkmcnt(0)
	v_add_f32_e32 v80, v80, v81
	global_store_dword v[82:83], v80, off
; #define PG8_GAS __attribute__((address_space(1)))
; __device__ __forceinline__ unsigned pk2_(float lo, float hi) { f32x2c_t v = {lo, hi}; bf16x2c_t b = __builtin_convertvector(v, bf16x2c_t); return __builtin_bit_cast(unsigned, b); }
;     __device__ __forceinline__ void operator()(const f32x4 (&acc)[2][2][4][2], const Unit& u, int wr, int wc, int fr, int fq) const {
;     ...
;         for (int ai = 0; ai < 2; ++ai)
; #pragma unroll
;             for (int m = 0; m < 4; ++m) {
;                 const int r = row0 + ai * HALF + m * 16; const size_t off = (size_t)r * 1024 + col0; float ss = 0.f;
; #pragma unroll
;                 for (int bj = 0; bj < 2; ++bj)
; #pragma unroll
;                     for (int n = 0; n < 2; ++n) {
;                         const u32x2v w0 = bsv[ai][m][bj][n]; f32x4 bs;
;                         bs[0] = __builtin_bit_cast(float, w0.x << 16); bs[1] = __builtin_bit_cast(float, w0.x & 0xffff0000u); bs[2] = __builtin_bit_cast(float, w0.y << 16); bs[3] = __builtin_bit_cast(float, w0.y & 0xffff0000u);
;                         const f32x4 v = bs + acc[ai][bj][m][n] * alpha;
;                         { u32x2v w; w.x = pk2_(v[0], v[1]); w.y = pk2_(v[2], v[3]); *(PG8_GAS u32x2v*)(hb + off + bj * HALF + n * 16) = w; }
;                         ss += (v[0] * v[0] + v[1] * v[1]) + (v[2] * v[2] + v[3] * v[3]);
;                     }
;                 ss += __shfl_xor(ss, 16); ss += __shfl_xor(ss, 32);
;                 if (fq == 0) ((PG8_GAS float*)parts)[(size_t)r * 16 + u.pn * 4 + wc] = ss;
;             }
.LBB0_777:
	s_or_b64 exec, exec, s[36:37]
	s_waitcnt vmcnt(28)
	v_lshlrev_b32_e32 v80, 16, v198
	s_waitcnt lgkmcnt(0)
	v_and_b32_e32 v81, 0xffff0000, v198
	v_lshlrev_b32_e32 v82, 16, v199
	v_and_b32_e32 v83, 0xffff0000, v199
	v_pk_fma_f32 v[76:77], v[76:77], 0.5, v[80:81] op_sel_hi:[1,0,1]
	v_pk_fma_f32 v[78:79], v[78:79], 0.5, v[82:83] op_sel_hi:[1,0,1]
	v_cvt_pk_bf16_f32 v80, v76, v77
	v_mul_f32_e32 v77, v77, v77
	v_lshl_add_u64 v[82:83], s[16:17], 0, v[194:195]
	v_fmac_f32_e32 v77, v76, v76
	v_mul_f32_e32 v76, v79, v79
	v_cvt_pk_bf16_f32 v81, v78, v79
	v_lshl_add_u64 v[82:83], v[138:139], 1, v[82:83]
	v_fmac_f32_e32 v76, v78, v78
	global_store_dwordx2 v[82:83], v[80:81], off
	v_add_f32_e32 v80, v77, v76
	v_lshlrev_b32_e32 v76, 16, v192
	v_and_b32_e32 v77, 0xffff0000, v192
	v_lshlrev_b32_e32 v78, 16, v193
	v_and_b32_e32 v79, 0xffff0000, v193
	v_pk_fma_f32 v[72:73], v[72:73], 0.5, v[76:77] op_sel_hi:[1,0,1]
	v_pk_fma_f32 v[74:75], v[74:75], 0.5, v[78:79] op_sel_hi:[1,0,1]
	v_cvt_pk_bf16_f32 v76, v72, v73
	v_mul_f32_e32 v73, v73, v73
	v_fmac_f32_e32 v73, v72, v72
	v_mul_f32_e32 v72, v75, v75
	v_fmac_f32_e32 v72, v74, v74
	v_add_f32_e32 v72, v73, v72
	v_add_f32_e32 v77, v80, v72
	v_lshlrev_b32_e32 v72, 16, v190
	v_and_b32_e32 v73, 0xffff0000, v190
	v_lshlrev_b32_e32 v78, 16, v191
	v_and_b32_e32 v79, 0xffff0000, v191
	v_pk_fma_f32 v[70:71], v[70:71], 0.5, v[78:79] op_sel_hi:[1,0,1]
	v_pk_fma_f32 v[68:69], v[68:69], 0.5, v[72:73] op_sel_hi:[1,0,1]
	v_mul_f32_e32 v73, v71, v71
	v_mul_f32_e32 v72, v69, v69
	v_fmac_f32_e32 v72, v68, v68
	v_fmac_f32_e32 v73, v70, v70
	v_add_f32_e32 v72, v72, v73
	v_add_f32_e32 v77, v77, v72
	v_lshlrev_b32_e32 v72, 16, v188
	v_and_b32_e32 v73, 0xffff0000, v188
	v_lshlrev_b32_e32 v78, 16, v189
	v_and_b32_e32 v79, 0xffff0000, v189
	v_pk_fma_f32 v[66:67], v[66:67], 0.5, v[78:79] op_sel_hi:[1,0,1]
	v_pk_fma_f32 v[72:73], v[64:65], 0.5, v[72:73] op_sel_hi:[1,0,1]
	v_mul_f32_e32 v65, v67, v67
	v_mul_f32_e32 v64, v73, v73
	v_fmac_f32_e32 v64, v72, v72
	v_fmac_f32_e32 v65, v66, v66
	v_add_f32_e32 v64, v64, v65
	v_add_f32_e32 v64, v77, v64
	v_mov_b32_e32 v65, v64
	s_nop 1
	v_permlane16_swap_b32_e32 v64, v65
	v_cvt_pk_bf16_f32 v68, v68, v69
	v_cvt_pk_bf16_f32 v69, v70, v71
	v_cvt_pk_bf16_f32 v77, v74, v75
	global_store_dwordx2 v[82:83], v[68:69], off offset:256
	s_waitcnt lgkmcnt(0)
	v_add_f32_e32 v64, v64, v65
	v_mov_b32_e32 v65, v64
	s_nop 1
	v_permlane32_swap_b32_e32 v64, v65
	v_cvt_pk_bf16_f32 v68, v72, v73
	v_cvt_pk_bf16_f32 v69, v66, v67
	global_store_dwordx2 v[82:83], v[76:77], off offset:32
	global_store_dwordx2 v[82:83], v[68:69], off offset:288
	s_and_saveexec_b64 s[36:37], vcc
	s_cbranch_execz .LBB0_779
	v_lshlrev_b64 v[66:67], 6, v[184:185]
	v_lshl_add_u64 v[66:67], s[18:19], 0, v[66:67]
	v_lshl_add_u64 v[66:67], s[34:35], 2, v[66:67]
	s_lshl_b32 s12, s48, 2
	v_lshl_add_u64 v[66:67], v[66:67], 0, s[12:13]
	s_waitcnt lgkmcnt(0)
	v_add_f32_e32 v64, v64, v65
	global_store_dword v[66:67], v64, off
.LBB0_779:
	s_or_b64 exec, exec, s[36:37]
	s_waitcnt vmcnt(28)
	v_lshlrev_b32_e32 v64, 16, v186
	s_waitcnt lgkmcnt(0)
	v_and_b32_e32 v65, 0xffff0000, v186
	v_lshlrev_b32_e32 v66, 16, v187
	v_and_b32_e32 v67, 0xffff0000, v187
	v_pk_fma_f32 v[60:61], v[60:61], 0.5, v[64:65] op_sel_hi:[1,0,1]
	v_pk_fma_f32 v[62:63], v[62:63], 0.5, v[66:67] op_sel_hi:[1,0,1]
	v_cvt_pk_bf16_f32 v64, v60, v61
	v_mul_f32_e32 v61, v61, v61
	v_lshl_add_u64 v[66:67], s[16:17], 0, v[182:183]
	v_fmac_f32_e32 v61, v60, v60
	v_mul_f32_e32 v60, v63, v63
	v_cvt_pk_bf16_f32 v65, v62, v63
	v_lshl_add_u64 v[66:67], v[138:139], 1, v[66:67]
	v_fmac_f32_e32 v60, v62, v62
	global_store_dwordx2 v[66:67], v[64:65], off
	v_add_f32_e32 v64, v61, v60
	v_lshlrev_b32_e32 v60, 16, v180
	v_and_b32_e32 v61, 0xffff0000, v180
	v_lshlrev_b32_e32 v62, 16, v181
	v_and_b32_e32 v63, 0xffff0000, v181
	v_pk_fma_f32 v[56:57], v[56:57], 0.5, v[60:61] op_sel_hi:[1,0,1]
	v_pk_fma_f32 v[58:59], v[58:59], 0.5, v[62:63] op_sel_hi:[1,0,1]
	v_cvt_pk_bf16_f32 v60, v56, v57
	v_mul_f32_e32 v57, v57, v57
	v_fmac_f32_e32 v57, v56, v56
	v_mul_f32_e32 v56, v59, v59
	v_fmac_f32_e32 v56, v58, v58
	v_add_f32_e32 v56, v57, v56
	v_add_f32_e32 v61, v64, v56
	v_lshlrev_b32_e32 v56, 16, v178
	v_and_b32_e32 v57, 0xffff0000, v178
	v_lshlrev_b32_e32 v62, 16, v179
	v_and_b32_e32 v63, 0xffff0000, v179
	v_pk_fma_f32 v[54:55], v[54:55], 0.5, v[62:63] op_sel_hi:[1,0,1]
	v_pk_fma_f32 v[52:53], v[52:53], 0.5, v[56:57] op_sel_hi:[1,0,1]
	v_mul_f32_e32 v57, v55, v55
	v_mul_f32_e32 v56, v53, v53
	v_fmac_f32_e32 v56, v52, v52
	v_fmac_f32_e32 v57, v54, v54
	v_add_f32_e32 v56, v56, v57
	v_add_f32_e32 v61, v61, v56
	v_lshlrev_b32_e32 v56, 16, v176
	v_and_b32_e32 v57, 0xffff0000, v176
	v_lshlrev_b32_e32 v62, 16, v177
	v_and_b32_e32 v63, 0xffff0000, v177
	v_pk_fma_f32 v[50:51], v[50:51], 0.5, v[62:63] op_sel_hi:[1,0,1]
	v_pk_fma_f32 v[56:57], v[48:49], 0.5, v[56:57] op_sel_hi:[1,0,1]
	v_mul_f32_e32 v49, v51, v51
	v_mul_f32_e32 v48, v57, v57
	v_fmac_f32_e32 v48, v56, v56
	v_fmac_f32_e32 v49, v50, v50
	v_add_f32_e32 v48, v48, v49
	v_add_f32_e32 v48, v61, v48
	v_mov_b32_e32 v49, v48
	s_nop 1
	v_permlane16_swap_b32_e32 v48, v49
	v_cvt_pk_bf16_f32 v52, v52, v53
	v_cvt_pk_bf16_f32 v53, v54, v55
	v_cvt_pk_bf16_f32 v61, v58, v59
	global_store_dwordx2 v[66:67], v[52:53], off offset:256
	s_waitcnt lgkmcnt(0)
	v_add_f32_e32 v48, v48, v49
	v_mov_b32_e32 v49, v48
	s_nop 1
	v_permlane32_swap_b32_e32 v48, v49
	v_cvt_pk_bf16_f32 v52, v56, v57
	v_cvt_pk_bf16_f32 v53, v50, v51
	global_store_dwordx2 v[66:67], v[60:61], off offset:32
	global_store_dwordx2 v[66:67], v[52:53], off offset:288
	s_and_saveexec_b64 s[36:37], vcc
	s_cbranch_execz .LBB0_781
	v_lshlrev_b64 v[50:51], 6, v[172:173]
	v_lshl_add_u64 v[50:51], s[18:19], 0, v[50:51]
	v_lshl_add_u64 v[50:51], s[34:35], 2, v[50:51]
	s_lshl_b32 s12, s48, 2
	v_lshl_add_u64 v[50:51], v[50:51], 0, s[12:13]
	s_waitcnt lgkmcnt(0)
	v_add_f32_e32 v48, v48, v49
	global_store_dword v[50:51], v48, off
; #define PG8_GAS __attribute__((address_space(1)))
; __device__ __forceinline__ unsigned pk2_(float lo, float hi) { f32x2c_t v = {lo, hi}; bf16x2c_t b = __builtin_convertvector(v, bf16x2c_t); return __builtin_bit_cast(unsigned, b); }
;     __device__ __forceinline__ void operator()(const f32x4 (&acc)[2][2][4][2], const Unit& u, int wr, int wc, int fr, int fq) const {
;     ...
;         for (int ai = 0; ai < 2; ++ai)
; #pragma unroll
;             for (int m = 0; m < 4; ++m) {
;                 const int r = row0 + ai * HALF + m * 16; const size_t off = (size_t)r * 1024 + col0; float ss = 0.f;
; #pragma unroll
;                 for (int bj = 0; bj < 2; ++bj)
; #pragma unroll
;                     for (int n = 0; n < 2; ++n) {
;                         const u32x2v w0 = bsv[ai][m][bj][n]; f32x4 bs;
;                         bs[0] = __builtin_bit_cast(float, w0.x << 16); bs[1] = __builtin_bit_cast(float, w0.x & 0xffff0000u); bs[2] = __builtin_bit_cast(float, w0.y << 16); bs[3] = __builtin_bit_cast(float, w0.y & 0xffff0000u);
;                         const f32x4 v = bs + acc[ai][bj][m][n] * alpha;
;                         { u32x2v w; w.x = pk2_(v[0], v[1]); w.y = pk2_(v[2], v[3]); *(PG8_GAS u32x2v*)(hb + off + bj * HALF + n * 16) = w; }
;                         ss += (v[0] * v[0] + v[1] * v[1]) + (v[2] * v[2] + v[3] * v[3]);
;                     }
;                 ss += __shfl_xor(ss, 16); ss += __shfl_xor(ss, 32);
;                 if (fq == 0) ((PG8_GAS float*)parts)[(size_t)r * 16 + u.pn * 4 + wc] = ss;
;             }
.LBB0_781:
	s_or_b64 exec, exec, s[36:37]
	s_waitcnt vmcnt(28)
	v_lshlrev_b32_e32 v48, 16, v174
	s_waitcnt lgkmcnt(0)
	v_and_b32_e32 v49, 0xffff0000, v174
	v_lshlrev_b32_e32 v50, 16, v175
	v_and_b32_e32 v51, 0xffff0000, v175
	v_pk_fma_f32 v[44:45], v[44:45], 0.5, v[48:49] op_sel_hi:[1,0,1]
	v_pk_fma_f32 v[46:47], v[46:47], 0.5, v[50:51] op_sel_hi:[1,0,1]
	v_cvt_pk_bf16_f32 v48, v44, v45
	v_mul_f32_e32 v45, v45, v45
	v_lshl_add_u64 v[50:51], s[16:17], 0, v[170:171]
	v_fmac_f32_e32 v45, v44, v44
	v_mul_f32_e32 v44, v47, v47
	v_cvt_pk_bf16_f32 v49, v46, v47
	v_lshl_add_u64 v[50:51], v[138:139], 1, v[50:51]
	v_fmac_f32_e32 v44, v46, v46
	global_store_dwordx2 v[50:51], v[48:49], off
	v_add_f32_e32 v48, v45, v44
	v_lshlrev_b32_e32 v44, 16, v168
	v_and_b32_e32 v45, 0xffff0000, v168
	v_lshlrev_b32_e32 v46, 16, v169
	v_and_b32_e32 v47, 0xffff0000, v169
	v_pk_fma_f32 v[40:41], v[40:41], 0.5, v[44:45] op_sel_hi:[1,0,1]
	v_pk_fma_f32 v[42:43], v[42:43], 0.5, v[46:47] op_sel_hi:[1,0,1]
	v_cvt_pk_bf16_f32 v44, v40, v41
	v_mul_f32_e32 v41, v41, v41
	v_fmac_f32_e32 v41, v40, v40
	v_mul_f32_e32 v40, v43, v43
	v_fmac_f32_e32 v40, v42, v42
	v_add_f32_e32 v40, v41, v40
	v_add_f32_e32 v45, v48, v40
	v_lshlrev_b32_e32 v40, 16, v166
	v_and_b32_e32 v41, 0xffff0000, v166
	v_lshlrev_b32_e32 v46, 16, v167
	v_and_b32_e32 v47, 0xffff0000, v167
	v_pk_fma_f32 v[38:39], v[38:39], 0.5, v[46:47] op_sel_hi:[1,0,1]
	v_pk_fma_f32 v[36:37], v[36:37], 0.5, v[40:41] op_sel_hi:[1,0,1]
	v_mul_f32_e32 v41, v39, v39
	v_mul_f32_e32 v40, v37, v37
	v_fmac_f32_e32 v40, v36, v36
	v_fmac_f32_e32 v41, v38, v38
	v_add_f32_e32 v40, v40, v41
	v_add_f32_e32 v45, v45, v40
	v_lshlrev_b32_e32 v40, 16, v164
	v_and_b32_e32 v41, 0xffff0000, v164
	v_lshlrev_b32_e32 v46, 16, v165
	v_and_b32_e32 v47, 0xffff0000, v165
	v_pk_fma_f32 v[34:35], v[34:35], 0.5, v[46:47] op_sel_hi:[1,0,1]
	v_pk_fma_f32 v[40:41], v[32:33], 0.5, v[40:41] op_sel_hi:[1,0,1]
	v_mul_f32_e32 v33, v35, v35
	v_mul_f32_e32 v32, v41, v41
	v_fmac_f32_e32 v32, v40, v40
	v_fmac_f32_e32 v33, v34, v34
	v_add_f32_e32 v32, v32, v33
	v_add_f32_e32 v32, v45, v32
	v_mov_b32_e32 v33, v32
	s_nop 1
	v_permlane16_swap_b32_e32 v32, v33
	v_cvt_pk_bf16_f32 v36, v36, v37
	v_cvt_pk_bf16_f32 v37, v38, v39
	v_cvt_pk_bf16_f32 v45, v42, v43
	global_store_dwordx2 v[50:51], v[36:37], off offset:256
	s_waitcnt lgkmcnt(0)
	v_add_f32_e32 v32, v32, v33
	v_mov_b32_e32 v33, v32
	s_nop 1
	v_permlane32_swap_b32_e32 v32, v33
	v_cvt_pk_bf16_f32 v36, v40, v41
	v_cvt_pk_bf16_f32 v37, v34, v35
	global_store_dwordx2 v[50:51], v[44:45], off offset:32
	global_store_dwordx2 v[50:51], v[36:37], off offset:288
	s_and_saveexec_b64 s[36:37], vcc
	s_cbranch_execz .LBB0_783
	v_lshlrev_b64 v[34:35], 6, v[160:161]
	v_lshl_add_u64 v[34:35], s[18:19], 0, v[34:35]
	v_lshl_add_u64 v[34:35], s[34:35], 2, v[34:35]
	s_lshl_b32 s12, s48, 2
	v_lshl_add_u64 v[34:35], v[34:35], 0, s[12:13]
	s_waitcnt lgkmcnt(0)
	v_add_f32_e32 v32, v32, v33
	global_store_dword v[34:35], v32, off
; #define PG8_GAS __attribute__((address_space(1)))
; __device__ __forceinline__ unsigned pk2_(float lo, float hi) { f32x2c_t v = {lo, hi}; bf16x2c_t b = __builtin_convertvector(v, bf16x2c_t); return __builtin_bit_cast(unsigned, b); }
;     __device__ __forceinline__ void operator()(const f32x4 (&acc)[2][2][4][2], const Unit& u, int wr, int wc, int fr, int fq) const {
;     ...
;         for (int ai = 0; ai < 2; ++ai)
; #pragma unroll
;             for (int m = 0; m < 4; ++m) {
;                 const int r = row0 + ai * HALF + m * 16; const size_t off = (size_t)r * 1024 + col0; float ss = 0.f;
; #pragma unroll
;                 for (int bj = 0; bj < 2; ++bj)
; #pragma unroll
;                     for (int n = 0; n < 2; ++n) {
;                         const u32x2v w0 = bsv[ai][m][bj][n]; f32x4 bs;
;                         bs[0] = __builtin_bit_cast(float, w0.x << 16); bs[1] = __builtin_bit_cast(float, w0.x & 0xffff0000u); bs[2] = __builtin_bit_cast(float, w0.y << 16); bs[3] = __builtin_bit_cast(float, w0.y & 0xffff0000u);
;                         const f32x4 v = bs + acc[ai][bj][m][n] * alpha;
;                         { u32x2v w; w.x = pk2_(v[0], v[1]); w.y = pk2_(v[2], v[3]); *(PG8_GAS u32x2v*)(hb + off + bj * HALF + n * 16) = w; }
;                         ss += (v[0] * v[0] + v[1] * v[1]) + (v[2] * v[2] + v[3] * v[3]);
;                     }
;                 ss += __shfl_xor(ss, 16); ss += __shfl_xor(ss, 32);
;                 if (fq == 0) ((PG8_GAS float*)parts)[(size_t)r * 16 + u.pn * 4 + wc] = ss;
;             }
.LBB0_783:
	s_or_b64 exec, exec, s[36:37]
	s_waitcnt vmcnt(28)
	v_lshlrev_b32_e32 v32, 16, v162
	s_waitcnt lgkmcnt(0)
	v_and_b32_e32 v33, 0xffff0000, v162
	v_lshlrev_b32_e32 v34, 16, v163
	v_and_b32_e32 v35, 0xffff0000, v163
	v_pk_fma_f32 v[28:29], v[28:29], 0.5, v[32:33] op_sel_hi:[1,0,1]
	v_pk_fma_f32 v[30:31], v[30:31], 0.5, v[34:35] op_sel_hi:[1,0,1]
	v_cvt_pk_bf16_f32 v32, v28, v29
	v_mul_f32_e32 v29, v29, v29
	v_lshl_add_u64 v[34:35], s[16:17], 0, v[158:159]
	v_fmac_f32_e32 v29, v28, v28
	v_mul_f32_e32 v28, v31, v31
	v_cvt_pk_bf16_f32 v33, v30, v31
	v_lshl_add_u64 v[34:35], v[138:139], 1, v[34:35]
	v_fmac_f32_e32 v28, v30, v30
	global_store_dwordx2 v[34:35], v[32:33], off
	v_add_f32_e32 v32, v29, v28
	v_lshlrev_b32_e32 v28, 16, v156
	v_and_b32_e32 v29, 0xffff0000, v156
	v_lshlrev_b32_e32 v30, 16, v157
	v_and_b32_e32 v31, 0xffff0000, v157
	v_pk_fma_f32 v[24:25], v[24:25], 0.5, v[28:29] op_sel_hi:[1,0,1]
	v_pk_fma_f32 v[26:27], v[26:27], 0.5, v[30:31] op_sel_hi:[1,0,1]
	v_cvt_pk_bf16_f32 v28, v24, v25
	v_mul_f32_e32 v25, v25, v25
	v_fmac_f32_e32 v25, v24, v24
	v_mul_f32_e32 v24, v27, v27
	v_fmac_f32_e32 v24, v26, v26
	v_add_f32_e32 v24, v25, v24
	v_add_f32_e32 v29, v32, v24
	v_lshlrev_b32_e32 v24, 16, v154
	v_and_b32_e32 v25, 0xffff0000, v154
	v_lshlrev_b32_e32 v30, 16, v155
	v_and_b32_e32 v31, 0xffff0000, v155
	v_pk_fma_f32 v[22:23], v[22:23], 0.5, v[30:31] op_sel_hi:[1,0,1]
	v_pk_fma_f32 v[20:21], v[20:21], 0.5, v[24:25] op_sel_hi:[1,0,1]
	v_mul_f32_e32 v25, v23, v23
	v_mul_f32_e32 v24, v21, v21
	v_fmac_f32_e32 v24, v20, v20
	v_fmac_f32_e32 v25, v22, v22
	v_add_f32_e32 v24, v24, v25
	v_add_f32_e32 v29, v29, v24
	v_lshlrev_b32_e32 v24, 16, v152
	v_and_b32_e32 v25, 0xffff0000, v152
	v_lshlrev_b32_e32 v30, 16, v153
	v_and_b32_e32 v31, 0xffff0000, v153
	v_pk_fma_f32 v[18:19], v[18:19], 0.5, v[30:31] op_sel_hi:[1,0,1]
	v_pk_fma_f32 v[24:25], v[16:17], 0.5, v[24:25] op_sel_hi:[1,0,1]
	v_mul_f32_e32 v17, v19, v19
	v_mul_f32_e32 v16, v25, v25
	v_fmac_f32_e32 v16, v24, v24
	v_fmac_f32_e32 v17, v18, v18
	v_add_f32_e32 v16, v16, v17
	v_add_f32_e32 v16, v29, v16
	v_mov_b32_e32 v17, v16
	s_nop 1
	v_permlane16_swap_b32_e32 v16, v17
	v_cvt_pk_bf16_f32 v20, v20, v21
	v_cvt_pk_bf16_f32 v21, v22, v23
	v_cvt_pk_bf16_f32 v29, v26, v27
	global_store_dwordx2 v[34:35], v[20:21], off offset:256
	s_waitcnt lgkmcnt(0)
	v_add_f32_e32 v16, v16, v17
	v_mov_b32_e32 v17, v16
	s_nop 1
	v_permlane32_swap_b32_e32 v16, v17
	v_cvt_pk_bf16_f32 v20, v24, v25
	v_cvt_pk_bf16_f32 v21, v18, v19
	global_store_dwordx2 v[34:35], v[28:29], off offset:32
	global_store_dwordx2 v[34:35], v[20:21], off offset:288
	s_and_saveexec_b64 s[36:37], vcc
	s_cbranch_execz .LBB0_785
	v_lshlrev_b64 v[18:19], 6, v[148:149]
	v_lshl_add_u64 v[18:19], s[18:19], 0, v[18:19]
	v_lshl_add_u64 v[18:19], s[34:35], 2, v[18:19]
	s_lshl_b32 s12, s48, 2
	v_lshl_add_u64 v[18:19], v[18:19], 0, s[12:13]
	s_waitcnt lgkmcnt(0)
	v_add_f32_e32 v16, v16, v17
	global_store_dword v[18:19], v16, off
.LBB0_785:
	s_or_b64 exec, exec, s[36:37]
	s_waitcnt vmcnt(28)
	v_lshlrev_b32_e32 v16, 16, v150
	s_waitcnt lgkmcnt(0)
	v_and_b32_e32 v17, 0xffff0000, v150
	v_lshlrev_b32_e32 v18, 16, v151
	v_and_b32_e32 v19, 0xffff0000, v151
	v_pk_fma_f32 v[12:13], v[12:13], 0.5, v[16:17] op_sel_hi:[1,0,1]
	v_pk_fma_f32 v[14:15], v[14:15], 0.5, v[18:19] op_sel_hi:[1,0,1]
	v_cvt_pk_bf16_f32 v16, v12, v13
	v_mul_f32_e32 v13, v13, v13
	v_lshl_add_u64 v[18:19], s[16:17], 0, v[146:147]
	v_fmac_f32_e32 v13, v12, v12
	v_mul_f32_e32 v12, v15, v15
	v_cvt_pk_bf16_f32 v17, v14, v15
	v_lshl_add_u64 v[18:19], v[138:139], 1, v[18:19]
	v_fmac_f32_e32 v12, v14, v14
	global_store_dwordx2 v[18:19], v[16:17], off
	v_add_f32_e32 v16, v13, v12
	v_lshlrev_b32_e32 v12, 16, v144
	v_and_b32_e32 v13, 0xffff0000, v144
	v_lshlrev_b32_e32 v14, 16, v145
	v_and_b32_e32 v15, 0xffff0000, v145
	v_pk_fma_f32 v[8:9], v[8:9], 0.5, v[12:13] op_sel_hi:[1,0,1]
	v_pk_fma_f32 v[10:11], v[10:11], 0.5, v[14:15] op_sel_hi:[1,0,1]
	v_cvt_pk_bf16_f32 v12, v8, v9
	v_mul_f32_e32 v9, v9, v9
	v_fmac_f32_e32 v9, v8, v8
	v_mul_f32_e32 v8, v11, v11
	v_fmac_f32_e32 v8, v10, v10
	v_add_f32_e32 v8, v9, v8
	v_add_f32_e32 v13, v16, v8
	v_lshlrev_b32_e32 v8, 16, v142
	v_and_b32_e32 v9, 0xffff0000, v142
	v_lshlrev_b32_e32 v14, 16, v143
	v_and_b32_e32 v15, 0xffff0000, v143
	v_pk_fma_f32 v[6:7], v[6:7], 0.5, v[14:15] op_sel_hi:[1,0,1]
	v_pk_fma_f32 v[4:5], v[4:5], 0.5, v[8:9] op_sel_hi:[1,0,1]
	v_mul_f32_e32 v9, v7, v7
	v_mul_f32_e32 v8, v5, v5
	v_fmac_f32_e32 v8, v4, v4
	v_fmac_f32_e32 v9, v6, v6
	v_add_f32_e32 v8, v8, v9
	v_add_f32_e32 v13, v13, v8
	v_lshlrev_b32_e32 v8, 16, v140
	v_and_b32_e32 v9, 0xffff0000, v140
	v_lshlrev_b32_e32 v14, 16, v141
	v_and_b32_e32 v15, 0xffff0000, v141
	v_pk_fma_f32 v[2:3], v[2:3], 0.5, v[14:15] op_sel_hi:[1,0,1]
	v_pk_fma_f32 v[8:9], v[0:1], 0.5, v[8:9] op_sel_hi:[1,0,1]
	v_mul_f32_e32 v1, v3, v3
	v_mul_f32_e32 v0, v9, v9
	v_fmac_f32_e32 v0, v8, v8
	v_fmac_f32_e32 v1, v2, v2
	v_add_f32_e32 v0, v0, v1
	v_add_f32_e32 v0, v13, v0
	v_mov_b32_e32 v1, v0
	s_nop 1
	v_permlane16_swap_b32_e32 v0, v1
	v_cvt_pk_bf16_f32 v4, v4, v5
	v_cvt_pk_bf16_f32 v5, v6, v7
	v_cvt_pk_bf16_f32 v13, v10, v11
	global_store_dwordx2 v[18:19], v[4:5], off offset:256
	s_waitcnt lgkmcnt(0)
	v_add_f32_e32 v0, v0, v1
	v_mov_b32_e32 v1, v0
	s_nop 1
	v_permlane32_swap_b32_e32 v0, v1
	v_cvt_pk_bf16_f32 v4, v8, v9
	v_cvt_pk_bf16_f32 v5, v2, v3
	global_store_dwordx2 v[18:19], v[12:13], off offset:32
	global_store_dwordx2 v[18:19], v[4:5], off offset:288
	s_and_saveexec_b64 s[36:37], vcc
	s_cbranch_execz .LBB0_787
	v_lshlrev_b64 v[2:3], 6, v[136:137]
	v_lshl_add_u64 v[2:3], s[18:19], 0, v[2:3]
	v_lshl_add_u64 v[2:3], s[34:35], 2, v[2:3]
	s_lshl_b32 s12, s48, 2
	v_lshl_add_u64 v[2:3], v[2:3], 0, s[12:13]
	s_waitcnt lgkmcnt(0)
	v_add_f32_e32 v0, v0, v1
	global_store_dword v[2:3], v0, off

; #define PG8_GAS __attribute__((address_space(1)))
; __device__ __forceinline__ unsigned pk2_(float lo, float hi) { f32x2c_t v = {lo, hi}; bf16x2c_t b = __builtin_convertvector(v, bf16x2c_t); return __builtin_bit_cast(unsigned, b); }
;     __device__ __forceinline__ void operator()(const f32x4 (&acc)[2][2][4][2], const Unit& u, int wr, int wc, int fr, int fq) const {
;         typedef unsigned u32x2v __attribute__((ext_vector_type(2)));
;         const int row0 = u.pm * BM + wr * 64 + fr, col0 = u.pn * BM + wc * 32 + 4 * fq;
;         u32x2v bsv[2][4][2][2];
; #pragma unroll
;         for (int ai = 0; ai < 2; ++ai)
; #pragma unroll
;             for (int m = 0; m < 4; ++m) { const size_t off = (size_t)(row0 + ai * HALF + m * 16) * 1024 + col0;
; #pragma unroll
;                 for (int bj = 0; bj < 2; ++bj)
; #pragma unroll
;                     for (int n = 0; n < 2; ++n) bsv[ai][m][bj][n] = *(const PG8_GAS u32x2v*)(hbase + off + bj * HALF + n * 16); }
; #pragma unroll
;         for (int ai = 0; ai < 2; ++ai)
; #pragma unroll
;             for (int m = 0; m < 4; ++m) {
;                 const int r = row0 + ai * HALF + m * 16; const size_t off = (size_t)r * 1024 + col0; float ss = 0.f;
; #pragma unroll
;                 for (int bj = 0; bj < 2; ++bj)
; #pragma unroll
;                     for (int n = 0; n < 2; ++n) {
;                         const u32x2v w0 = bsv[ai][m][bj][n]; f32x4 bs;
;                         bs[0] = __builtin_bit_cast(float, w0.x << 16); bs[1] = __builtin_bit_cast(float, w0.x & 0xffff0000u); bs[2] = __builtin_bit_cast(float, w0.y << 16); bs[3] = __builtin_bit_cast(float, w0.y & 0xffff0000u);
;                         const f32x4 v = bs + acc[ai][bj][m][n] * alpha;
;                         { u32x2v w; w.x = pk2_(v[0], v[1]); w.y = pk2_(v[2], v[3]); *(PG8_GAS u32x2v*)(hb + off + bj * HALF + n * 16) = w; }
;                         ss += (v[0] * v[0] + v[1] * v[1]) + (v[2] * v[2] + v[3] * v[3]);
;                     }
;                 ss += __shfl_xor(ss, 16); ss += __shfl_xor(ss, 32);
;                 if (fq == 0) ((PG8_GAS float*)parts)[(size_t)r * 16 + u.pn * 4 + wc] = ss;
;             }
.LBB0_1378:
	s_lshl_b32 s27, s36, 8
	v_mov_b32_e32 v136, v252
	s_add_i32 s27, s27, s54
	v_cmp_lt_i32_e32 vcc, v227, v226
	v_and_or_b32 v220, v136, 15, s27
	s_lshl_b32 s27, s10, 8
	v_bfe_u32 v244, v136, 4, 2
	s_or_b32 s27, s27, s55
	v_lshl_or_b32 v138, v244, 2, s27
	v_ashrrev_i32_e32 v139, 31, v138
	v_lshlrev_b64 v[224:225], 1, v[138:139]
	v_ashrrev_i32_e32 v221, 31, v220
	v_lshl_add_u64 v[140:141], s[12:13], 0, v[224:225]
	v_lshlrev_b64 v[234:235], 11, v[220:221]
	v_lshl_add_u64 v[136:137], v[140:141], 0, v[234:235]
	global_load_dwordx2 v[236:237], v[136:137], off
	global_load_dwordx2 v[238:239], v[136:137], off offset:32
	global_load_dwordx2 v[240:241], v[136:137], off offset:256
	global_load_dwordx2 v[242:243], v[136:137], off offset:288
	v_or_b32_e32 v208, 16, v220
	v_ashrrev_i32_e32 v209, 31, v208
	v_or_b32_e32 v196, 32, v220
	v_lshlrev_b64 v[218:219], 11, v[208:209]
	v_ashrrev_i32_e32 v197, 31, v196
	v_or_b32_e32 v184, 48, v220
	v_lshl_add_u64 v[136:137], v[140:141], 0, v[218:219]
	v_lshlrev_b64 v[206:207], 11, v[196:197]
	v_ashrrev_i32_e32 v185, 31, v184
	v_add_u32_e32 v172, 0x80, v220
	global_load_dwordx2 v[222:223], v[136:137], off
	global_load_dwordx2 v[216:217], v[136:137], off offset:32
	global_load_dwordx2 v[214:215], v[136:137], off offset:256
	global_load_dwordx2 v[212:213], v[136:137], off offset:288
	v_lshl_add_u64 v[136:137], v[140:141], 0, v[206:207]
	v_lshlrev_b64 v[194:195], 11, v[184:185]
	v_ashrrev_i32_e32 v173, 31, v172
	v_add_u32_e32 v160, 0x90, v220
	global_load_dwordx2 v[210:211], v[136:137], off
	global_load_dwordx2 v[204:205], v[136:137], off offset:32
	global_load_dwordx2 v[202:203], v[136:137], off offset:256
	global_load_dwordx2 v[200:201], v[136:137], off offset:288
	v_lshl_add_u64 v[136:137], v[140:141], 0, v[194:195]
	v_lshlrev_b64 v[182:183], 11, v[172:173]
	v_ashrrev_i32_e32 v161, 31, v160
	v_add_u32_e32 v148, 0xa0, v220
	global_load_dwordx2 v[198:199], v[136:137], off
	global_load_dwordx2 v[192:193], v[136:137], off offset:32
	global_load_dwordx2 v[190:191], v[136:137], off offset:256
	global_load_dwordx2 v[188:189], v[136:137], off offset:288
	v_lshl_add_u64 v[136:137], v[140:141], 0, v[182:183]
	v_lshlrev_b64 v[170:171], 11, v[160:161]
	v_ashrrev_i32_e32 v149, 31, v148
	global_load_dwordx2 v[186:187], v[136:137], off
	global_load_dwordx2 v[180:181], v[136:137], off offset:32
	global_load_dwordx2 v[178:179], v[136:137], off offset:256
	global_load_dwordx2 v[176:177], v[136:137], off offset:288
	v_lshl_add_u64 v[136:137], v[140:141], 0, v[170:171]
	v_lshlrev_b64 v[158:159], 11, v[148:149]
	global_load_dwordx2 v[174:175], v[136:137], off
	global_load_dwordx2 v[168:169], v[136:137], off offset:32
	global_load_dwordx2 v[166:167], v[136:137], off offset:256
	global_load_dwordx2 v[164:165], v[136:137], off offset:288
	v_lshl_add_u64 v[136:137], v[140:141], 0, v[158:159]
	global_load_dwordx2 v[162:163], v[136:137], off
	global_load_dwordx2 v[156:157], v[136:137], off offset:32
	global_load_dwordx2 v[154:155], v[136:137], off offset:256
	global_load_dwordx2 v[152:153], v[136:137], off offset:288
	v_add_u32_e32 v136, 0xb0, v220
	v_ashrrev_i32_e32 v137, 31, v136
	v_lshlrev_b64 v[146:147], 11, v[136:137]
	v_lshl_add_u64 v[140:141], v[140:141], 0, v[146:147]
	global_load_dwordx2 v[150:151], v[140:141], off
	global_load_dwordx2 v[144:145], v[140:141], off offset:32
	global_load_dwordx2 v[142:143], v[140:141], off offset:256
	s_nop 0
	global_load_dwordx2 v[140:141], v[140:141], off offset:288
	v_xor_b32_e32 v245, 32, v253
	v_cndmask_b32_e32 v232, v253, v227, vcc
	v_cmp_lt_i32_e32 vcc, v245, v226
	v_lshlrev_b32_e32 v233, 2, v232
	v_lshl_add_u64 v[234:235], s[12:13], 0, v[234:235]
	v_cndmask_b32_e32 v232, v253, v245, vcc
	v_cmp_eq_u32_e32 vcc, 0, v244
	v_lshl_add_u64 v[224:225], v[234:235], 0, v[224:225]
	v_lshlrev_b32_e32 v232, 2, v232
	s_lshl_b32 s36, s10, 2
	s_ashr_i32 s37, s36, 31
	s_waitcnt vmcnt(28)
	v_lshlrev_b32_e32 v244, 16, v236
	v_and_b32_e32 v245, 0xffff0000, v236
	v_lshlrev_b32_e32 v236, 16, v237
	v_and_b32_e32 v237, 0xffff0000, v237
	v_pk_add_f32 v[124:125], v[124:125], v[244:245]
	v_pk_add_f32 v[126:127], v[126:127], v[236:237]
	v_cvt_pk_bf16_f32 v236, v124, v125
	v_mul_f32_e32 v125, v125, v125
	v_fmac_f32_e32 v125, v124, v124
	v_mul_f32_e32 v124, v127, v127
	v_fmac_f32_e32 v124, v126, v126
	v_add_f32_e32 v234, v125, v124
	v_lshlrev_b32_e32 v124, 16, v238
	v_and_b32_e32 v125, 0xffff0000, v238
	v_cvt_pk_bf16_f32 v237, v126, v127
	v_lshlrev_b32_e32 v126, 16, v239
	v_and_b32_e32 v127, 0xffff0000, v239
	v_pk_add_f32 v[120:121], v[120:121], v[124:125]
	v_pk_add_f32 v[122:123], v[122:123], v[126:127]
	v_cvt_pk_bf16_f32 v124, v120, v121
	v_mul_f32_e32 v121, v121, v121
	v_fmac_f32_e32 v121, v120, v120
	v_mul_f32_e32 v120, v123, v123
	v_fmac_f32_e32 v120, v122, v122
	v_add_f32_e32 v120, v121, v120
	v_add_f32_e32 v125, v234, v120
	v_lshlrev_b32_e32 v120, 16, v240
	v_and_b32_e32 v121, 0xffff0000, v240
	v_lshlrev_b32_e32 v126, 16, v241
	v_and_b32_e32 v127, 0xffff0000, v241
	v_pk_add_f32 v[118:119], v[118:119], v[126:127]
	v_pk_add_f32 v[116:117], v[116:117], v[120:121]
	v_mul_f32_e32 v121, v119, v119
	v_mul_f32_e32 v120, v117, v117
	v_fmac_f32_e32 v120, v116, v116
	v_fmac_f32_e32 v121, v118, v118
	v_add_f32_e32 v120, v120, v121
	v_add_f32_e32 v125, v125, v120
	v_lshlrev_b32_e32 v120, 16, v242
	v_and_b32_e32 v121, 0xffff0000, v242
	v_lshlrev_b32_e32 v126, 16, v243
	v_and_b32_e32 v127, 0xffff0000, v243
	v_pk_add_f32 v[114:115], v[114:115], v[126:127]
	v_pk_add_f32 v[120:121], v[112:113], v[120:121]
	v_mul_f32_e32 v113, v115, v115
	v_mul_f32_e32 v112, v121, v121
	v_fmac_f32_e32 v112, v120, v120
	v_fmac_f32_e32 v113, v114, v114
	v_add_f32_e32 v112, v112, v113
	v_add_f32_e32 v112, v125, v112
	v_mov_b32_e32 v113, v112
	s_nop 1
	v_permlane16_swap_b32_e32 v112, v113
	v_cvt_pk_bf16_f32 v116, v116, v117
	v_cvt_pk_bf16_f32 v117, v118, v119
	v_cvt_pk_bf16_f32 v125, v122, v123
	global_store_dwordx2 v[224:225], v[116:117], off offset:256
	s_waitcnt lgkmcnt(0)
	v_add_f32_e32 v112, v112, v113
	v_mov_b32_e32 v113, v112
	s_nop 1
	v_permlane32_swap_b32_e32 v112, v113
	v_cvt_pk_bf16_f32 v116, v120, v121
	v_cvt_pk_bf16_f32 v117, v114, v115
	global_store_dwordx2 v[224:225], v[236:237], off
	global_store_dwordx2 v[224:225], v[124:125], off offset:32
	global_store_dwordx2 v[224:225], v[116:117], off offset:288
	s_and_saveexec_b64 s[38:39], vcc
	s_cbranch_execz .LBB0_1380
	v_lshlrev_b64 v[114:115], 6, v[220:221]
	v_lshl_add_u64 v[114:115], s[14:15], 0, v[114:115]
	v_lshl_add_u64 v[114:115], s[36:37], 2, v[114:115]
	s_lshl_b32 s10, s53, 2
	v_lshl_add_u64 v[114:115], v[114:115], 0, s[10:11]
	s_waitcnt lgkmcnt(0)
	v_add_f32_e32 v112, v112, v113
	global_store_dword v[114:115], v112, off
; #define PG8_GAS __attribute__((address_space(1)))
; __device__ __forceinline__ unsigned pk2_(float lo, float hi) { f32x2c_t v = {lo, hi}; bf16x2c_t b = __builtin_convertvector(v, bf16x2c_t); return __builtin_bit_cast(unsigned, b); }
;     __device__ __forceinline__ void operator()(const f32x4 (&acc)[2][2][4][2], const Unit& u, int wr, int wc, int fr, int fq) const {
;     ...
;         for (int ai = 0; ai < 2; ++ai)
; #pragma unroll
;             for (int m = 0; m < 4; ++m) {
;                 const int r = row0 + ai * HALF + m * 16; const size_t off = (size_t)r * 1024 + col0; float ss = 0.f;
; #pragma unroll
;                 for (int bj = 0; bj < 2; ++bj)
; #pragma unroll
;                     for (int n = 0; n < 2; ++n) {
;                         const u32x2v w0 = bsv[ai][m][bj][n]; f32x4 bs;
;                         bs[0] = __builtin_bit_cast(float, w0.x << 16); bs[1] = __builtin_bit_cast(float, w0.x & 0xffff0000u); bs[2] = __builtin_bit_cast(float, w0.y << 16); bs[3] = __builtin_bit_cast(float, w0.y & 0xffff0000u);
;                         const f32x4 v = bs + acc[ai][bj][m][n] * alpha;
;                         { u32x2v w; w.x = pk2_(v[0], v[1]); w.y = pk2_(v[2], v[3]); *(PG8_GAS u32x2v*)(hb + off + bj * HALF + n * 16) = w; }
;                         ss += (v[0] * v[0] + v[1] * v[1]) + (v[2] * v[2] + v[3] * v[3]);
;                     }
;                 ss += __shfl_xor(ss, 16); ss += __shfl_xor(ss, 32);
;                 if (fq == 0) ((PG8_GAS float*)parts)[(size_t)r * 16 + u.pn * 4 + wc] = ss;
;             }
.LBB0_1380:
	s_or_b64 exec, exec, s[38:39]
	s_waitcnt vmcnt(28)
	v_lshlrev_b32_e32 v112, 16, v222
	s_waitcnt lgkmcnt(0)
	v_and_b32_e32 v113, 0xffff0000, v222
	v_lshlrev_b32_e32 v114, 16, v223
	v_and_b32_e32 v115, 0xffff0000, v223
	v_pk_add_f32 v[108:109], v[108:109], v[112:113]
	v_pk_add_f32 v[110:111], v[110:111], v[114:115]
	v_cvt_pk_bf16_f32 v112, v108, v109
	v_mul_f32_e32 v109, v109, v109
	v_lshl_add_u64 v[114:115], s[12:13], 0, v[218:219]
	v_fmac_f32_e32 v109, v108, v108
	v_mul_f32_e32 v108, v111, v111
	v_cvt_pk_bf16_f32 v113, v110, v111
	v_lshl_add_u64 v[114:115], v[138:139], 1, v[114:115]
	v_fmac_f32_e32 v108, v110, v110
	global_store_dwordx2 v[114:115], v[112:113], off
	v_add_f32_e32 v112, v109, v108
	v_lshlrev_b32_e32 v108, 16, v216
	v_and_b32_e32 v109, 0xffff0000, v216
	v_lshlrev_b32_e32 v110, 16, v217
	v_and_b32_e32 v111, 0xffff0000, v217
	v_pk_add_f32 v[104:105], v[104:105], v[108:109]
	v_pk_add_f32 v[106:107], v[106:107], v[110:111]
	v_cvt_pk_bf16_f32 v108, v104, v105
	v_mul_f32_e32 v105, v105, v105
	v_fmac_f32_e32 v105, v104, v104
	v_mul_f32_e32 v104, v107, v107
	v_fmac_f32_e32 v104, v106, v106
	v_add_f32_e32 v104, v105, v104
	v_add_f32_e32 v109, v112, v104
	v_lshlrev_b32_e32 v104, 16, v214
	v_and_b32_e32 v105, 0xffff0000, v214
	v_lshlrev_b32_e32 v110, 16, v215
	v_and_b32_e32 v111, 0xffff0000, v215
	v_pk_add_f32 v[102:103], v[102:103], v[110:111]
	v_pk_add_f32 v[100:101], v[100:101], v[104:105]
	v_mul_f32_e32 v105, v103, v103
	v_mul_f32_e32 v104, v101, v101
	v_fmac_f32_e32 v104, v100, v100
	v_fmac_f32_e32 v105, v102, v102
	v_add_f32_e32 v104, v104, v105
	v_add_f32_e32 v109, v109, v104
	v_lshlrev_b32_e32 v104, 16, v212
	v_and_b32_e32 v105, 0xffff0000, v212
	v_lshlrev_b32_e32 v110, 16, v213
	v_and_b32_e32 v111, 0xffff0000, v213
	v_pk_add_f32 v[98:99], v[98:99], v[110:111]
	v_pk_add_f32 v[104:105], v[96:97], v[104:105]
	v_mul_f32_e32 v97, v99, v99
	v_mul_f32_e32 v96, v105, v105
	v_fmac_f32_e32 v96, v104, v104
	v_fmac_f32_e32 v97, v98, v98
	v_add_f32_e32 v96, v96, v97
	v_add_f32_e32 v96, v109, v96
	v_mov_b32_e32 v97, v96
	s_nop 1
	v_permlane16_swap_b32_e32 v96, v97
	v_cvt_pk_bf16_f32 v100, v100, v101
	v_cvt_pk_bf16_f32 v101, v102, v103
	v_cvt_pk_bf16_f32 v109, v106, v107
	global_store_dwordx2 v[114:115], v[100:101], off offset:256
	s_waitcnt lgkmcnt(0)
	v_add_f32_e32 v96, v96, v97
	v_mov_b32_e32 v97, v96
	s_nop 1
	v_permlane32_swap_b32_e32 v96, v97
	v_cvt_pk_bf16_f32 v100, v104, v105
	v_cvt_pk_bf16_f32 v101, v98, v99
	global_store_dwordx2 v[114:115], v[108:109], off offset:32
	global_store_dwordx2 v[114:115], v[100:101], off offset:288
	s_and_saveexec_b64 s[38:39], vcc
	s_cbranch_execz .LBB0_1382
	v_lshlrev_b64 v[98:99], 6, v[208:209]
	v_lshl_add_u64 v[98:99], s[14:15], 0, v[98:99]
	v_lshl_add_u64 v[98:99], s[36:37], 2, v[98:99]
	s_lshl_b32 s10, s53, 2
	v_lshl_add_u64 v[98:99], v[98:99], 0, s[10:11]
	s_waitcnt lgkmcnt(0)
	v_add_f32_e32 v96, v96, v97
	global_store_dword v[98:99], v96, off
.LBB0_1382:
	s_or_b64 exec, exec, s[38:39]
	s_waitcnt vmcnt(28)
	v_lshlrev_b32_e32 v96, 16, v210
	s_waitcnt lgkmcnt(0)
	v_and_b32_e32 v97, 0xffff0000, v210
	v_lshlrev_b32_e32 v98, 16, v211
	v_and_b32_e32 v99, 0xffff0000, v211
	v_pk_add_f32 v[92:93], v[92:93], v[96:97]
	v_pk_add_f32 v[94:95], v[94:95], v[98:99]
	v_cvt_pk_bf16_f32 v96, v92, v93
	v_mul_f32_e32 v93, v93, v93
	v_lshl_add_u64 v[98:99], s[12:13], 0, v[206:207]
	v_fmac_f32_e32 v93, v92, v92
	v_mul_f32_e32 v92, v95, v95
	v_cvt_pk_bf16_f32 v97, v94, v95
	v_lshl_add_u64 v[98:99], v[138:139], 1, v[98:99]
	v_fmac_f32_e32 v92, v94, v94
	global_store_dwordx2 v[98:99], v[96:97], off
	v_add_f32_e32 v96, v93, v92
	v_lshlrev_b32_e32 v92, 16, v204
	v_and_b32_e32 v93, 0xffff0000, v204
	v_lshlrev_b32_e32 v94, 16, v205
	v_and_b32_e32 v95, 0xffff0000, v205
	v_pk_add_f32 v[88:89], v[88:89], v[92:93]
	v_pk_add_f32 v[90:91], v[90:91], v[94:95]
	v_cvt_pk_bf16_f32 v92, v88, v89
	v_mul_f32_e32 v89, v89, v89
	v_fmac_f32_e32 v89, v88, v88
	v_mul_f32_e32 v88, v91, v91
	v_fmac_f32_e32 v88, v90, v90
	v_add_f32_e32 v88, v89, v88
	v_add_f32_e32 v93, v96, v88
	v_lshlrev_b32_e32 v88, 16, v202
	v_and_b32_e32 v89, 0xffff0000, v202
	v_lshlrev_b32_e32 v94, 16, v203
	v_and_b32_e32 v95, 0xffff0000, v203
	v_pk_add_f32 v[86:87], v[86:87], v[94:95]
	v_pk_add_f32 v[84:85], v[84:85], v[88:89]
	v_mul_f32_e32 v89, v87, v87
	v_mul_f32_e32 v88, v85, v85
	v_fmac_f32_e32 v88, v84, v84
	v_fmac_f32_e32 v89, v86, v86
	v_add_f32_e32 v88, v88, v89
	v_add_f32_e32 v93, v93, v88
	v_lshlrev_b32_e32 v88, 16, v200
	v_and_b32_e32 v89, 0xffff0000, v200
	v_lshlrev_b32_e32 v94, 16, v201
	v_and_b32_e32 v95, 0xffff0000, v201
	v_pk_add_f32 v[82:83], v[82:83], v[94:95]
	v_pk_add_f32 v[88:89], v[80:81], v[88:89]
	v_mul_f32_e32 v81, v83, v83
	v_mul_f32_e32 v80, v89, v89
	v_fmac_f32_e32 v80, v88, v88
	v_fmac_f32_e32 v81, v82, v82
	v_add_f32_e32 v80, v80, v81
	v_add_f32_e32 v80, v93, v80
	v_mov_b32_e32 v81, v80
	s_nop 1
	v_permlane16_swap_b32_e32 v80, v81
	v_cvt_pk_bf16_f32 v84, v84, v85
	v_cvt_pk_bf16_f32 v85, v86, v87
	v_cvt_pk_bf16_f32 v93, v90, v91
	global_store_dwordx2 v[98:99], v[84:85], off offset:256
	s_waitcnt lgkmcnt(0)
	v_add_f32_e32 v80, v80, v81
	v_mov_b32_e32 v81, v80
	s_nop 1
	v_permlane32_swap_b32_e32 v80, v81
	v_cvt_pk_bf16_f32 v84, v88, v89
	v_cvt_pk_bf16_f32 v85, v82, v83
	global_store_dwordx2 v[98:99], v[92:93], off offset:32
	global_store_dwordx2 v[98:99], v[84:85], off offset:288
	s_and_saveexec_b64 s[38:39], vcc
	s_cbranch_execz .LBB0_1384
	v_lshlrev_b64 v[82:83], 6, v[196:197]
	v_lshl_add_u64 v[82:83], s[14:15], 0, v[82:83]
	v_lshl_add_u64 v[82:83], s[36:37], 2, v[82:83]
	s_lshl_b32 s10, s53, 2
	v_lshl_add_u64 v[82:83], v[82:83], 0, s[10:11]
	s_waitcnt lgkmcnt(0)
	v_add_f32_e32 v80, v80, v81
	global_store_dword v[82:83], v80, off
; #define PG8_GAS __attribute__((address_space(1)))
; __device__ __forceinline__ unsigned pk2_(float lo, float hi) { f32x2c_t v = {lo, hi}; bf16x2c_t b = __builtin_convertvector(v, bf16x2c_t); return __builtin_bit_cast(unsigned, b); }
;     __device__ __forceinline__ void operator()(const f32x4 (&acc)[2][2][4][2], const Unit& u, int wr, int wc, int fr, int fq) const {
;     ...
;         for (int ai = 0; ai < 2; ++ai)
; #pragma unroll
;             for (int m = 0; m < 4; ++m) {
;                 const int r = row0 + ai * HALF + m * 16; const size_t off = (size_t)r * 1024 + col0; float ss = 0.f;
; #pragma unroll
;                 for (int bj = 0; bj < 2; ++bj)
; #pragma unroll
;                     for (int n = 0; n < 2; ++n) {
;                         const u32x2v w0 = bsv[ai][m][bj][n]; f32x4 bs;
;                         bs[0] = __builtin_bit_cast(float, w0.x << 16); bs[1] = __builtin_bit_cast(float, w0.x & 0xffff0000u); bs[2] = __builtin_bit_cast(float, w0.y << 16); bs[3] = __builtin_bit_cast(float, w0.y & 0xffff0000u);
;                         const f32x4 v = bs + acc[ai][bj][m][n] * alpha;
;                         { u32x2v w; w.x = pk2_(v[0], v[1]); w.y = pk2_(v[2], v[3]); *(PG8_GAS u32x2v*)(hb + off + bj * HALF + n * 16) = w; }
;                         ss += (v[0] * v[0] + v[1] * v[1]) + (v[2] * v[2] + v[3] * v[3]);
;                     }
;                 ss += __shfl_xor(ss, 16); ss += __shfl_xor(ss, 32);
;                 if (fq == 0) ((PG8_GAS float*)parts)[(size_t)r * 16 + u.pn * 4 + wc] = ss;
;             }
.LBB0_1384:
	s_or_b64 exec, exec, s[38:39]
	s_waitcnt vmcnt(28)
	v_lshlrev_b32_e32 v80, 16, v198
	s_waitcnt lgkmcnt(0)
	v_and_b32_e32 v81, 0xffff0000, v198
	v_lshlrev_b32_e32 v82, 16, v199
	v_and_b32_e32 v83, 0xffff0000, v199
	v_pk_add_f32 v[76:77], v[76:77], v[80:81]
	v_pk_add_f32 v[78:79], v[78:79], v[82:83]
	v_cvt_pk_bf16_f32 v80, v76, v77
	v_mul_f32_e32 v77, v77, v77
	v_lshl_add_u64 v[82:83], s[12:13], 0, v[194:195]
	v_fmac_f32_e32 v77, v76, v76
	v_mul_f32_e32 v76, v79, v79
	v_cvt_pk_bf16_f32 v81, v78, v79
	v_lshl_add_u64 v[82:83], v[138:139], 1, v[82:83]
	v_fmac_f32_e32 v76, v78, v78
	global_store_dwordx2 v[82:83], v[80:81], off
	v_add_f32_e32 v80, v77, v76
	v_lshlrev_b32_e32 v76, 16, v192
	v_and_b32_e32 v77, 0xffff0000, v192
	v_lshlrev_b32_e32 v78, 16, v193
	v_and_b32_e32 v79, 0xffff0000, v193
	v_pk_add_f32 v[72:73], v[72:73], v[76:77]
	v_pk_add_f32 v[74:75], v[74:75], v[78:79]
	v_cvt_pk_bf16_f32 v76, v72, v73
	v_mul_f32_e32 v73, v73, v73
	v_fmac_f32_e32 v73, v72, v72
	v_mul_f32_e32 v72, v75, v75
	v_fmac_f32_e32 v72, v74, v74
	v_add_f32_e32 v72, v73, v72
	v_add_f32_e32 v77, v80, v72
	v_lshlrev_b32_e32 v72, 16, v190
	v_and_b32_e32 v73, 0xffff0000, v190
	v_lshlrev_b32_e32 v78, 16, v191
	v_and_b32_e32 v79, 0xffff0000, v191
	v_pk_add_f32 v[70:71], v[70:71], v[78:79]
	v_pk_add_f32 v[68:69], v[68:69], v[72:73]
	v_mul_f32_e32 v73, v71, v71
	v_mul_f32_e32 v72, v69, v69
	v_fmac_f32_e32 v72, v68, v68
	v_fmac_f32_e32 v73, v70, v70
	v_add_f32_e32 v72, v72, v73
	v_add_f32_e32 v77, v77, v72
	v_lshlrev_b32_e32 v72, 16, v188
	v_and_b32_e32 v73, 0xffff0000, v188
	v_lshlrev_b32_e32 v78, 16, v189
	v_and_b32_e32 v79, 0xffff0000, v189
	v_pk_add_f32 v[66:67], v[66:67], v[78:79]
	v_pk_add_f32 v[72:73], v[64:65], v[72:73]
	v_mul_f32_e32 v65, v67, v67
	v_mul_f32_e32 v64, v73, v73
	v_fmac_f32_e32 v64, v72, v72
	v_fmac_f32_e32 v65, v66, v66
	v_add_f32_e32 v64, v64, v65
	v_add_f32_e32 v64, v77, v64
	v_mov_b32_e32 v65, v64
	s_nop 1
	v_permlane16_swap_b32_e32 v64, v65
	v_cvt_pk_bf16_f32 v68, v68, v69
	v_cvt_pk_bf16_f32 v69, v70, v71
	v_cvt_pk_bf16_f32 v77, v74, v75
	global_store_dwordx2 v[82:83], v[68:69], off offset:256
	s_waitcnt lgkmcnt(0)
	v_add_f32_e32 v64, v64, v65
	v_mov_b32_e32 v65, v64
	s_nop 1
	v_permlane32_swap_b32_e32 v64, v65
	v_cvt_pk_bf16_f32 v68, v72, v73
	v_cvt_pk_bf16_f32 v69, v66, v67
	global_store_dwordx2 v[82:83], v[76:77], off offset:32
	global_store_dwordx2 v[82:83], v[68:69], off offset:288
	s_and_saveexec_b64 s[38:39], vcc
	s_cbranch_execz .LBB0_1386
	v_lshlrev_b64 v[66:67], 6, v[184:185]
	v_lshl_add_u64 v[66:67], s[14:15], 0, v[66:67]
	v_lshl_add_u64 v[66:67], s[36:37], 2, v[66:67]
	s_lshl_b32 s10, s53, 2
	v_lshl_add_u64 v[66:67], v[66:67], 0, s[10:11]
	s_waitcnt lgkmcnt(0)
	v_add_f32_e32 v64, v64, v65
	global_store_dword v[66:67], v64, off
.LBB0_1386:
	s_or_b64 exec, exec, s[38:39]
	s_waitcnt vmcnt(28)
	v_lshlrev_b32_e32 v64, 16, v186
	s_waitcnt lgkmcnt(0)
	v_and_b32_e32 v65, 0xffff0000, v186
	v_lshlrev_b32_e32 v66, 16, v187
	v_and_b32_e32 v67, 0xffff0000, v187
	v_pk_add_f32 v[60:61], v[60:61], v[64:65]
	v_pk_add_f32 v[62:63], v[62:63], v[66:67]
	v_cvt_pk_bf16_f32 v64, v60, v61
	v_mul_f32_e32 v61, v61, v61
	v_lshl_add_u64 v[66:67], s[12:13], 0, v[182:183]
	v_fmac_f32_e32 v61, v60, v60
	v_mul_f32_e32 v60, v63, v63
	v_cvt_pk_bf16_f32 v65, v62, v63
	v_lshl_add_u64 v[66:67], v[138:139], 1, v[66:67]
	v_fmac_f32_e32 v60, v62, v62
	global_store_dwordx2 v[66:67], v[64:65], off
	v_add_f32_e32 v64, v61, v60
	v_lshlrev_b32_e32 v60, 16, v180
	v_and_b32_e32 v61, 0xffff0000, v180
	v_lshlrev_b32_e32 v62, 16, v181
	v_and_b32_e32 v63, 0xffff0000, v181
	v_pk_add_f32 v[56:57], v[56:57], v[60:61]
	v_pk_add_f32 v[58:59], v[58:59], v[62:63]
	v_cvt_pk_bf16_f32 v60, v56, v57
	v_mul_f32_e32 v57, v57, v57
	v_fmac_f32_e32 v57, v56, v56
	v_mul_f32_e32 v56, v59, v59
	v_fmac_f32_e32 v56, v58, v58
	v_add_f32_e32 v56, v57, v56
	v_add_f32_e32 v61, v64, v56
	v_lshlrev_b32_e32 v56, 16, v178
	v_and_b32_e32 v57, 0xffff0000, v178
	v_lshlrev_b32_e32 v62, 16, v179
	v_and_b32_e32 v63, 0xffff0000, v179
	v_pk_add_f32 v[54:55], v[54:55], v[62:63]
	v_pk_add_f32 v[52:53], v[52:53], v[56:57]
	v_mul_f32_e32 v57, v55, v55
	v_mul_f32_e32 v56, v53, v53
	v_fmac_f32_e32 v56, v52, v52
	v_fmac_f32_e32 v57, v54, v54
	v_add_f32_e32 v56, v56, v57
	v_add_f32_e32 v61, v61, v56
	v_lshlrev_b32_e32 v56, 16, v176
	v_and_b32_e32 v57, 0xffff0000, v176
	v_lshlrev_b32_e32 v62, 16, v177
	v_and_b32_e32 v63, 0xffff0000, v177
	v_pk_add_f32 v[50:51], v[50:51], v[62:63]
	v_pk_add_f32 v[56:57], v[48:49], v[56:57]
	v_mul_f32_e32 v49, v51, v51
	v_mul_f32_e32 v48, v57, v57
	v_fmac_f32_e32 v48, v56, v56
	v_fmac_f32_e32 v49, v50, v50
	v_add_f32_e32 v48, v48, v49
	v_add_f32_e32 v48, v61, v48
	v_mov_b32_e32 v49, v48
	s_nop 1
	v_permlane16_swap_b32_e32 v48, v49
	v_cvt_pk_bf16_f32 v52, v52, v53
	v_cvt_pk_bf16_f32 v53, v54, v55
	v_cvt_pk_bf16_f32 v61, v58, v59
	global_store_dwordx2 v[66:67], v[52:53], off offset:256
	s_waitcnt lgkmcnt(0)
	v_add_f32_e32 v48, v48, v49
	v_mov_b32_e32 v49, v48
	s_nop 1
	v_permlane32_swap_b32_e32 v48, v49
	v_cvt_pk_bf16_f32 v52, v56, v57
	v_cvt_pk_bf16_f32 v53, v50, v51
	global_store_dwordx2 v[66:67], v[60:61], off offset:32
	global_store_dwordx2 v[66:67], v[52:53], off offset:288
	s_and_saveexec_b64 s[38:39], vcc
	s_cbranch_execz .LBB0_1388
	v_lshlrev_b64 v[50:51], 6, v[172:173]
	v_lshl_add_u64 v[50:51], s[14:15], 0, v[50:51]
	v_lshl_add_u64 v[50:51], s[36:37], 2, v[50:51]
	s_lshl_b32 s10, s53, 2
	v_lshl_add_u64 v[50:51], v[50:51], 0, s[10:11]
	s_waitcnt lgkmcnt(0)
	v_add_f32_e32 v48, v48, v49
	global_store_dword v[50:51], v48, off
; #define PG8_GAS __attribute__((address_space(1)))
; __device__ __forceinline__ unsigned pk2_(float lo, float hi) { f32x2c_t v = {lo, hi}; bf16x2c_t b = __builtin_convertvector(v, bf16x2c_t); return __builtin_bit_cast(unsigned, b); }
;     __device__ __forceinline__ void operator()(const f32x4 (&acc)[2][2][4][2], const Unit& u, int wr, int wc, int fr, int fq) const {
;     ...
;         for (int ai = 0; ai < 2; ++ai)
; #pragma unroll
;             for (int m = 0; m < 4; ++m) {
;                 const int r = row0 + ai * HALF + m * 16; const size_t off = (size_t)r * 1024 + col0; float ss = 0.f;
; #pragma unroll
;                 for (int bj = 0; bj < 2; ++bj)
; #pragma unroll
;                     for (int n = 0; n < 2; ++n) {
;                         const u32x2v w0 = bsv[ai][m][bj][n]; f32x4 bs;
;                         bs[0] = __builtin_bit_cast(float, w0.x << 16); bs[1] = __builtin_bit_cast(float, w0.x & 0xffff0000u); bs[2] = __builtin_bit_cast(float, w0.y << 16); bs[3] = __builtin_bit_cast(float, w0.y & 0xffff0000u);
;                         const f32x4 v = bs + acc[ai][bj][m][n] * alpha;
;                         { u32x2v w; w.x = pk2_(v[0], v[1]); w.y = pk2_(v[2], v[3]); *(PG8_GAS u32x2v*)(hb + off + bj * HALF + n * 16) = w; }
;                         ss += (v[0] * v[0] + v[1] * v[1]) + (v[2] * v[2] + v[3] * v[3]);
;                     }
;                 ss += __shfl_xor(ss, 16); ss += __shfl_xor(ss, 32);
;                 if (fq == 0) ((PG8_GAS float*)parts)[(size_t)r * 16 + u.pn * 4 + wc] = ss;
;             }
.LBB0_1388:
	s_or_b64 exec, exec, s[38:39]
	s_waitcnt vmcnt(28)
	v_lshlrev_b32_e32 v48, 16, v174
	s_waitcnt lgkmcnt(0)
	v_and_b32_e32 v49, 0xffff0000, v174
	v_lshlrev_b32_e32 v50, 16, v175
	v_and_b32_e32 v51, 0xffff0000, v175
	v_pk_add_f32 v[44:45], v[44:45], v[48:49]
	v_pk_add_f32 v[46:47], v[46:47], v[50:51]
	v_cvt_pk_bf16_f32 v48, v44, v45
	v_mul_f32_e32 v45, v45, v45
	v_lshl_add_u64 v[50:51], s[12:13], 0, v[170:171]
	v_fmac_f32_e32 v45, v44, v44
	v_mul_f32_e32 v44, v47, v47
	v_cvt_pk_bf16_f32 v49, v46, v47
	v_lshl_add_u64 v[50:51], v[138:139], 1, v[50:51]
	v_fmac_f32_e32 v44, v46, v46
	global_store_dwordx2 v[50:51], v[48:49], off
	v_add_f32_e32 v48, v45, v44
	v_lshlrev_b32_e32 v44, 16, v168
	v_and_b32_e32 v45, 0xffff0000, v168
	v_lshlrev_b32_e32 v46, 16, v169
	v_and_b32_e32 v47, 0xffff0000, v169
	v_pk_add_f32 v[40:41], v[40:41], v[44:45]
	v_pk_add_f32 v[42:43], v[42:43], v[46:47]
	v_cvt_pk_bf16_f32 v44, v40, v41
	v_mul_f32_e32 v41, v41, v41
	v_fmac_f32_e32 v41, v40, v40
	v_mul_f32_e32 v40, v43, v43
	v_fmac_f32_e32 v40, v42, v42
	v_add_f32_e32 v40, v41, v40
	v_add_f32_e32 v45, v48, v40
	v_lshlrev_b32_e32 v40, 16, v166
	v_and_b32_e32 v41, 0xffff0000, v166
	v_lshlrev_b32_e32 v46, 16, v167
	v_and_b32_e32 v47, 0xffff0000, v167
	v_pk_add_f32 v[38:39], v[38:39], v[46:47]
	v_pk_add_f32 v[36:37], v[36:37], v[40:41]
	v_mul_f32_e32 v41, v39, v39
	v_mul_f32_e32 v40, v37, v37
	v_fmac_f32_e32 v40, v36, v36
	v_fmac_f32_e32 v41, v38, v38
	v_add_f32_e32 v40, v40, v41
	v_add_f32_e32 v45, v45, v40
	v_lshlrev_b32_e32 v40, 16, v164
	v_and_b32_e32 v41, 0xffff0000, v164
	v_lshlrev_b32_e32 v46, 16, v165
	v_and_b32_e32 v47, 0xffff0000, v165
	v_pk_add_f32 v[34:35], v[34:35], v[46:47]
	v_pk_add_f32 v[40:41], v[32:33], v[40:41]
	v_mul_f32_e32 v33, v35, v35
	v_mul_f32_e32 v32, v41, v41
	v_fmac_f32_e32 v32, v40, v40
	v_fmac_f32_e32 v33, v34, v34
	v_add_f32_e32 v32, v32, v33
	v_add_f32_e32 v32, v45, v32
	v_mov_b32_e32 v33, v32
	s_nop 1
	v_permlane16_swap_b32_e32 v32, v33
	v_cvt_pk_bf16_f32 v36, v36, v37
	v_cvt_pk_bf16_f32 v37, v38, v39
	v_cvt_pk_bf16_f32 v45, v42, v43
	global_store_dwordx2 v[50:51], v[36:37], off offset:256
	s_waitcnt lgkmcnt(0)
	v_add_f32_e32 v32, v32, v33
	v_mov_b32_e32 v33, v32
	s_nop 1
	v_permlane32_swap_b32_e32 v32, v33
	v_cvt_pk_bf16_f32 v36, v40, v41
	v_cvt_pk_bf16_f32 v37, v34, v35
	global_store_dwordx2 v[50:51], v[44:45], off offset:32
	global_store_dwordx2 v[50:51], v[36:37], off offset:288
	s_and_saveexec_b64 s[38:39], vcc
	s_cbranch_execz .LBB0_1390
	v_lshlrev_b64 v[34:35], 6, v[160:161]
	v_lshl_add_u64 v[34:35], s[14:15], 0, v[34:35]
	v_lshl_add_u64 v[34:35], s[36:37], 2, v[34:35]
	s_lshl_b32 s10, s53, 2
	v_lshl_add_u64 v[34:35], v[34:35], 0, s[10:11]
	s_waitcnt lgkmcnt(0)
	v_add_f32_e32 v32, v32, v33
	global_store_dword v[34:35], v32, off
; #define PG8_GAS __attribute__((address_space(1)))
; __device__ __forceinline__ unsigned pk2_(float lo, float hi) { f32x2c_t v = {lo, hi}; bf16x2c_t b = __builtin_convertvector(v, bf16x2c_t); return __builtin_bit_cast(unsigned, b); }
;     __device__ __forceinline__ void operator()(const f32x4 (&acc)[2][2][4][2], const Unit& u, int wr, int wc, int fr, int fq) const {
;     ...
;         for (int ai = 0; ai < 2; ++ai)
; #pragma unroll
;             for (int m = 0; m < 4; ++m) {
;                 const int r = row0 + ai * HALF + m * 16; const size_t off = (size_t)r * 1024 + col0; float ss = 0.f;
; #pragma unroll
;                 for (int bj = 0; bj < 2; ++bj)
; #pragma unroll
;                     for (int n = 0; n < 2; ++n) {
;                         const u32x2v w0 = bsv[ai][m][bj][n]; f32x4 bs;
;                         bs[0] = __builtin_bit_cast(float, w0.x << 16); bs[1] = __builtin_bit_cast(float, w0.x & 0xffff0000u); bs[2] = __builtin_bit_cast(float, w0.y << 16); bs[3] = __builtin_bit_cast(float, w0.y & 0xffff0000u);
;                         const f32x4 v = bs + acc[ai][bj][m][n] * alpha;
;                         { u32x2v w; w.x = pk2_(v[0], v[1]); w.y = pk2_(v[2], v[3]); *(PG8_GAS u32x2v*)(hb + off + bj * HALF + n * 16) = w; }
;                         ss += (v[0] * v[0] + v[1] * v[1]) + (v[2] * v[2] + v[3] * v[3]);
;                     }
;                 ss += __shfl_xor(ss, 16); ss += __shfl_xor(ss, 32);
;                 if (fq == 0) ((PG8_GAS float*)parts)[(size_t)r * 16 + u.pn * 4 + wc] = ss;
;             }
.LBB0_1390:
	s_or_b64 exec, exec, s[38:39]
	s_waitcnt vmcnt(28)
	v_lshlrev_b32_e32 v32, 16, v162
	s_waitcnt lgkmcnt(0)
	v_and_b32_e32 v33, 0xffff0000, v162
	v_lshlrev_b32_e32 v34, 16, v163
	v_and_b32_e32 v35, 0xffff0000, v163
	v_pk_add_f32 v[28:29], v[28:29], v[32:33]
	v_pk_add_f32 v[30:31], v[30:31], v[34:35]
	v_cvt_pk_bf16_f32 v32, v28, v29
	v_mul_f32_e32 v29, v29, v29
	v_lshl_add_u64 v[34:35], s[12:13], 0, v[158:159]
	v_fmac_f32_e32 v29, v28, v28
	v_mul_f32_e32 v28, v31, v31
	v_cvt_pk_bf16_f32 v33, v30, v31
	v_lshl_add_u64 v[34:35], v[138:139], 1, v[34:35]
	v_fmac_f32_e32 v28, v30, v30
	global_store_dwordx2 v[34:35], v[32:33], off
	v_add_f32_e32 v32, v29, v28
	v_lshlrev_b32_e32 v28, 16, v156
	v_and_b32_e32 v29, 0xffff0000, v156
	v_lshlrev_b32_e32 v30, 16, v157
	v_and_b32_e32 v31, 0xffff0000, v157
	v_pk_add_f32 v[24:25], v[24:25], v[28:29]
	v_pk_add_f32 v[26:27], v[26:27], v[30:31]
	v_cvt_pk_bf16_f32 v28, v24, v25
	v_mul_f32_e32 v25, v25, v25
	v_fmac_f32_e32 v25, v24, v24
	v_mul_f32_e32 v24, v27, v27
	v_fmac_f32_e32 v24, v26, v26
	v_add_f32_e32 v24, v25, v24
	v_add_f32_e32 v29, v32, v24
	v_lshlrev_b32_e32 v24, 16, v154
	v_and_b32_e32 v25, 0xffff0000, v154
	v_lshlrev_b32_e32 v30, 16, v155
	v_and_b32_e32 v31, 0xffff0000, v155
	v_pk_add_f32 v[22:23], v[22:23], v[30:31]
	v_pk_add_f32 v[20:21], v[20:21], v[24:25]
	v_mul_f32_e32 v25, v23, v23
	v_mul_f32_e32 v24, v21, v21
	v_fmac_f32_e32 v24, v20, v20
	v_fmac_f32_e32 v25, v22, v22
	v_add_f32_e32 v24, v24, v25
	v_add_f32_e32 v29, v29, v24
	v_lshlrev_b32_e32 v24, 16, v152
	v_and_b32_e32 v25, 0xffff0000, v152
	v_lshlrev_b32_e32 v30, 16, v153
	v_and_b32_e32 v31, 0xffff0000, v153
	v_pk_add_f32 v[18:19], v[18:19], v[30:31]
	v_pk_add_f32 v[24:25], v[16:17], v[24:25]
	v_mul_f32_e32 v17, v19, v19
	v_mul_f32_e32 v16, v25, v25
	v_fmac_f32_e32 v16, v24, v24
	v_fmac_f32_e32 v17, v18, v18
	v_add_f32_e32 v16, v16, v17
	v_add_f32_e32 v16, v29, v16
	v_mov_b32_e32 v17, v16
	s_nop 1
	v_permlane16_swap_b32_e32 v16, v17
	v_cvt_pk_bf16_f32 v20, v20, v21
	v_cvt_pk_bf16_f32 v21, v22, v23
	v_cvt_pk_bf16_f32 v29, v26, v27
	global_store_dwordx2 v[34:35], v[20:21], off offset:256
	s_waitcnt lgkmcnt(0)
	v_add_f32_e32 v16, v16, v17
	v_mov_b32_e32 v17, v16
	s_nop 1
	v_permlane32_swap_b32_e32 v16, v17
	v_cvt_pk_bf16_f32 v20, v24, v25
	v_cvt_pk_bf16_f32 v21, v18, v19
	global_store_dwordx2 v[34:35], v[28:29], off offset:32
	global_store_dwordx2 v[34:35], v[20:21], off offset:288
	s_and_saveexec_b64 s[38:39], vcc
	s_cbranch_execz .LBB0_1392
	v_lshlrev_b64 v[18:19], 6, v[148:149]
	v_lshl_add_u64 v[18:19], s[14:15], 0, v[18:19]
	v_lshl_add_u64 v[18:19], s[36:37], 2, v[18:19]
	s_lshl_b32 s10, s53, 2
	v_lshl_add_u64 v[18:19], v[18:19], 0, s[10:11]
	s_waitcnt lgkmcnt(0)
	v_add_f32_e32 v16, v16, v17
	global_store_dword v[18:19], v16, off
.LBB0_1392:
	s_or_b64 exec, exec, s[38:39]
	s_waitcnt vmcnt(28)
	v_lshlrev_b32_e32 v16, 16, v150
	s_waitcnt lgkmcnt(0)
	v_and_b32_e32 v17, 0xffff0000, v150
	v_lshlrev_b32_e32 v18, 16, v151
	v_and_b32_e32 v19, 0xffff0000, v151
	v_pk_add_f32 v[12:13], v[12:13], v[16:17]
	v_pk_add_f32 v[14:15], v[14:15], v[18:19]
	v_cvt_pk_bf16_f32 v16, v12, v13
	v_mul_f32_e32 v13, v13, v13
	v_lshl_add_u64 v[18:19], s[12:13], 0, v[146:147]
	v_fmac_f32_e32 v13, v12, v12
	v_mul_f32_e32 v12, v15, v15
	v_cvt_pk_bf16_f32 v17, v14, v15
	v_lshl_add_u64 v[18:19], v[138:139], 1, v[18:19]
	v_fmac_f32_e32 v12, v14, v14
	global_store_dwordx2 v[18:19], v[16:17], off
	v_add_f32_e32 v16, v13, v12
	v_lshlrev_b32_e32 v12, 16, v144
	v_and_b32_e32 v13, 0xffff0000, v144
	v_lshlrev_b32_e32 v14, 16, v145
	v_and_b32_e32 v15, 0xffff0000, v145
	v_pk_add_f32 v[8:9], v[8:9], v[12:13]
	v_pk_add_f32 v[10:11], v[10:11], v[14:15]
	v_cvt_pk_bf16_f32 v12, v8, v9
	v_mul_f32_e32 v9, v9, v9
	v_fmac_f32_e32 v9, v8, v8
	v_mul_f32_e32 v8, v11, v11
	v_fmac_f32_e32 v8, v10, v10
	v_add_f32_e32 v8, v9, v8
	v_add_f32_e32 v13, v16, v8
	v_lshlrev_b32_e32 v8, 16, v142
	v_and_b32_e32 v9, 0xffff0000, v142
	v_lshlrev_b32_e32 v14, 16, v143
	v_and_b32_e32 v15, 0xffff0000, v143
	v_pk_add_f32 v[6:7], v[6:7], v[14:15]
	v_pk_add_f32 v[4:5], v[4:5], v[8:9]
	v_mul_f32_e32 v9, v7, v7
	v_mul_f32_e32 v8, v5, v5
	v_fmac_f32_e32 v8, v4, v4
	v_fmac_f32_e32 v9, v6, v6
	v_add_f32_e32 v8, v8, v9
	v_add_f32_e32 v13, v13, v8
	v_lshlrev_b32_e32 v8, 16, v140
	v_and_b32_e32 v9, 0xffff0000, v140
	v_lshlrev_b32_e32 v14, 16, v141
	v_and_b32_e32 v15, 0xffff0000, v141
	v_pk_add_f32 v[2:3], v[2:3], v[14:15]
	v_pk_add_f32 v[8:9], v[0:1], v[8:9]
	v_mul_f32_e32 v1, v3, v3
	v_mul_f32_e32 v0, v9, v9
	v_fmac_f32_e32 v0, v8, v8
	v_fmac_f32_e32 v1, v2, v2
	v_add_f32_e32 v0, v0, v1
	v_add_f32_e32 v0, v13, v0
	v_mov_b32_e32 v1, v0
	s_nop 1
	v_permlane16_swap_b32_e32 v0, v1
	v_cvt_pk_bf16_f32 v4, v4, v5
	v_cvt_pk_bf16_f32 v5, v6, v7
	v_cvt_pk_bf16_f32 v13, v10, v11
	global_store_dwordx2 v[18:19], v[4:5], off offset:256
	s_waitcnt lgkmcnt(0)
	v_add_f32_e32 v0, v0, v1
	v_mov_b32_e32 v1, v0
	s_nop 1
	v_permlane32_swap_b32_e32 v0, v1
	v_cvt_pk_bf16_f32 v4, v8, v9
	v_cvt_pk_bf16_f32 v5, v2, v3
	global_store_dwordx2 v[18:19], v[12:13], off offset:32
	global_store_dwordx2 v[18:19], v[4:5], off offset:288
	s_and_saveexec_b64 s[38:39], vcc
	s_cbranch_execz .LBB0_1394
	v_lshlrev_b64 v[2:3], 6, v[136:137]
	v_lshl_add_u64 v[2:3], s[14:15], 0, v[2:3]
	v_lshl_add_u64 v[2:3], s[36:37], 2, v[2:3]
	s_lshl_b32 s10, s53, 2
	v_lshl_add_u64 v[2:3], v[2:3], 0, s[10:11]
	s_waitcnt lgkmcnt(0)
	v_add_f32_e32 v0, v0, v1
	global_store_dword v[2:3], v0, off

; #define PG8_GAS __attribute__((address_space(1)))
; __device__ __forceinline__ unsigned pk2_(float lo, float hi) { f32x2c_t v = {lo, hi}; bf16x2c_t b = __builtin_convertvector(v, bf16x2c_t); return __builtin_bit_cast(unsigned, b); }
;     __device__ __forceinline__ void operator()(const f32x4 (&acc)[2][2][4][2], const Unit& u, int wr, int wc, int fr, int fq) const {
;         typedef unsigned u32x2v __attribute__((ext_vector_type(2)));
;         const int row0 = u.pm * BM + wr * 64 + fr, col0 = u.pn * BM + wc * 32 + 4 * fq;
;         u32x2v bsv[2][4][2][2];
; #pragma unroll
;         for (int ai = 0; ai < 2; ++ai)
; #pragma unroll
;             for (int m = 0; m < 4; ++m) { const size_t off = (size_t)(row0 + ai * HALF + m * 16) * 1024 + col0;
; #pragma unroll
;                 for (int bj = 0; bj < 2; ++bj)
; #pragma unroll
;                     for (int n = 0; n < 2; ++n) bsv[ai][m][bj][n] = *(const PG8_GAS u32x2v*)(hbase + off + bj * HALF + n * 16); }
; #pragma unroll
;         for (int ai = 0; ai < 2; ++ai)
; #pragma unroll
;             for (int m = 0; m < 4; ++m) {
;                 const int r = row0 + ai * HALF + m * 16; const size_t off = (size_t)r * 1024 + col0; float ss = 0.f;
; #pragma unroll
;                 for (int bj = 0; bj < 2; ++bj)
; #pragma unroll
;                     for (int n = 0; n < 2; ++n) {
;                         const u32x2v w0 = bsv[ai][m][bj][n]; f32x4 bs;
;                         bs[0] = __builtin_bit_cast(float, w0.x << 16); bs[1] = __builtin_bit_cast(float, w0.x & 0xffff0000u); bs[2] = __builtin_bit_cast(float, w0.y << 16); bs[3] = __builtin_bit_cast(float, w0.y & 0xffff0000u);
;                         const f32x4 v = bs + acc[ai][bj][m][n] * alpha;
;                         { u32x2v w; w.x = pk2_(v[0], v[1]); w.y = pk2_(v[2], v[3]); *(PG8_GAS u32x2v*)(hb + off + bj * HALF + n * 16) = w; }
;                         ss += (v[0] * v[0] + v[1] * v[1]) + (v[2] * v[2] + v[3] * v[3]);
;                     }
;                 ss += __shfl_xor(ss, 16); ss += __shfl_xor(ss, 32);
;                 if (fq == 0) ((PG8_GAS float*)parts)[(size_t)r * 16 + u.pn * 4 + wc] = ss;
;             }
.LBB0_1735:
	s_lshl_b32 s30, s57, 8
	v_mov_b32_e32 v136, v252
	s_add_i32 s30, s30, s48
	v_cmp_lt_i32_e32 vcc, v227, v226
	v_and_or_b32 v220, v136, 15, s30
	s_lshl_b32 s30, s12, 8
	v_bfe_u32 v244, v136, 4, 2
	s_or_b32 s30, s30, s49
	v_lshl_or_b32 v138, v244, 2, s30
	v_ashrrev_i32_e32 v139, 31, v138
	v_lshlrev_b64 v[224:225], 1, v[138:139]
	v_ashrrev_i32_e32 v221, 31, v220
	v_lshl_add_u64 v[140:141], s[14:15], 0, v[224:225]
	v_lshlrev_b64 v[234:235], 11, v[220:221]
	v_lshl_add_u64 v[136:137], v[140:141], 0, v[234:235]
	global_load_dwordx2 v[236:237], v[136:137], off
	global_load_dwordx2 v[238:239], v[136:137], off offset:32
	global_load_dwordx2 v[240:241], v[136:137], off offset:256
	global_load_dwordx2 v[242:243], v[136:137], off offset:288
	v_or_b32_e32 v208, 16, v220
	v_ashrrev_i32_e32 v209, 31, v208
	v_or_b32_e32 v196, 32, v220
	v_lshlrev_b64 v[218:219], 11, v[208:209]
	v_ashrrev_i32_e32 v197, 31, v196
	v_or_b32_e32 v184, 48, v220
	v_lshl_add_u64 v[136:137], v[140:141], 0, v[218:219]
	v_lshlrev_b64 v[206:207], 11, v[196:197]
	v_ashrrev_i32_e32 v185, 31, v184
	v_add_u32_e32 v172, 0x80, v220
	global_load_dwordx2 v[222:223], v[136:137], off
	global_load_dwordx2 v[216:217], v[136:137], off offset:32
	global_load_dwordx2 v[214:215], v[136:137], off offset:256
	global_load_dwordx2 v[212:213], v[136:137], off offset:288
	v_lshl_add_u64 v[136:137], v[140:141], 0, v[206:207]
	v_lshlrev_b64 v[194:195], 11, v[184:185]
	v_ashrrev_i32_e32 v173, 31, v172
	v_add_u32_e32 v160, 0x90, v220
	global_load_dwordx2 v[210:211], v[136:137], off
	global_load_dwordx2 v[204:205], v[136:137], off offset:32
	global_load_dwordx2 v[202:203], v[136:137], off offset:256
	global_load_dwordx2 v[200:201], v[136:137], off offset:288
	v_lshl_add_u64 v[136:137], v[140:141], 0, v[194:195]
	v_lshlrev_b64 v[182:183], 11, v[172:173]
	v_ashrrev_i32_e32 v161, 31, v160
	v_add_u32_e32 v148, 0xa0, v220
	global_load_dwordx2 v[198:199], v[136:137], off
	global_load_dwordx2 v[192:193], v[136:137], off offset:32
	global_load_dwordx2 v[190:191], v[136:137], off offset:256
	global_load_dwordx2 v[188:189], v[136:137], off offset:288
	v_lshl_add_u64 v[136:137], v[140:141], 0, v[182:183]
	v_lshlrev_b64 v[170:171], 11, v[160:161]
	v_ashrrev_i32_e32 v149, 31, v148
	global_load_dwordx2 v[186:187], v[136:137], off
	global_load_dwordx2 v[180:181], v[136:137], off offset:32
	global_load_dwordx2 v[178:179], v[136:137], off offset:256
	global_load_dwordx2 v[176:177], v[136:137], off offset:288
	v_lshl_add_u64 v[136:137], v[140:141], 0, v[170:171]
	v_lshlrev_b64 v[158:159], 11, v[148:149]
	global_load_dwordx2 v[174:175], v[136:137], off
	global_load_dwordx2 v[168:169], v[136:137], off offset:32
	global_load_dwordx2 v[166:167], v[136:137], off offset:256
	global_load_dwordx2 v[164:165], v[136:137], off offset:288
	v_lshl_add_u64 v[136:137], v[140:141], 0, v[158:159]
	global_load_dwordx2 v[162:163], v[136:137], off
	global_load_dwordx2 v[156:157], v[136:137], off offset:32
	global_load_dwordx2 v[154:155], v[136:137], off offset:256
	global_load_dwordx2 v[152:153], v[136:137], off offset:288
	v_add_u32_e32 v136, 0xb0, v220
	v_ashrrev_i32_e32 v137, 31, v136
	v_lshlrev_b64 v[146:147], 11, v[136:137]
	v_lshl_add_u64 v[140:141], v[140:141], 0, v[146:147]
	global_load_dwordx2 v[150:151], v[140:141], off
	global_load_dwordx2 v[144:145], v[140:141], off offset:32
	global_load_dwordx2 v[142:143], v[140:141], off offset:256
	s_nop 0
	global_load_dwordx2 v[140:141], v[140:141], off offset:288
	v_xor_b32_e32 v245, 32, v253
	v_cndmask_b32_e32 v232, v253, v227, vcc
	v_cmp_lt_i32_e32 vcc, v245, v226
	v_lshlrev_b32_e32 v233, 2, v232
	v_lshl_add_u64 v[234:235], s[14:15], 0, v[234:235]
	v_cndmask_b32_e32 v232, v253, v245, vcc
	v_cmp_eq_u32_e32 vcc, 0, v244
	v_lshl_add_u64 v[224:225], v[234:235], 0, v[224:225]
	v_lshlrev_b32_e32 v232, 2, v232
	s_lshl_b32 s30, s12, 2
	s_ashr_i32 s31, s30, 31
	s_waitcnt vmcnt(28)
	v_lshlrev_b32_e32 v244, 16, v236
	v_and_b32_e32 v245, 0xffff0000, v236
	v_lshlrev_b32_e32 v236, 16, v237
	v_and_b32_e32 v237, 0xffff0000, v237
	v_pk_fma_f32 v[124:125], v[124:125], 0.5, v[244:245] op_sel_hi:[1,0,1]
	v_pk_fma_f32 v[126:127], v[126:127], 0.5, v[236:237] op_sel_hi:[1,0,1]
	v_cvt_pk_bf16_f32 v236, v124, v125
	v_mul_f32_e32 v125, v125, v125
	v_fmac_f32_e32 v125, v124, v124
	v_mul_f32_e32 v124, v127, v127
	v_fmac_f32_e32 v124, v126, v126
	v_add_f32_e32 v234, v125, v124
	v_lshlrev_b32_e32 v124, 16, v238
	v_and_b32_e32 v125, 0xffff0000, v238
	v_cvt_pk_bf16_f32 v237, v126, v127
	v_lshlrev_b32_e32 v126, 16, v239
	v_and_b32_e32 v127, 0xffff0000, v239
	v_pk_fma_f32 v[120:121], v[120:121], 0.5, v[124:125] op_sel_hi:[1,0,1]
	v_pk_fma_f32 v[122:123], v[122:123], 0.5, v[126:127] op_sel_hi:[1,0,1]
	v_cvt_pk_bf16_f32 v124, v120, v121
	v_mul_f32_e32 v121, v121, v121
	v_fmac_f32_e32 v121, v120, v120
	v_mul_f32_e32 v120, v123, v123
	v_fmac_f32_e32 v120, v122, v122
	v_add_f32_e32 v120, v121, v120
	v_add_f32_e32 v125, v234, v120
	v_lshlrev_b32_e32 v120, 16, v240
	v_and_b32_e32 v121, 0xffff0000, v240
	v_lshlrev_b32_e32 v126, 16, v241
	v_and_b32_e32 v127, 0xffff0000, v241
	v_pk_fma_f32 v[118:119], v[118:119], 0.5, v[126:127] op_sel_hi:[1,0,1]
	v_pk_fma_f32 v[116:117], v[116:117], 0.5, v[120:121] op_sel_hi:[1,0,1]
	v_mul_f32_e32 v121, v119, v119
	v_mul_f32_e32 v120, v117, v117
	v_fmac_f32_e32 v120, v116, v116
	v_fmac_f32_e32 v121, v118, v118
	v_add_f32_e32 v120, v120, v121
	v_add_f32_e32 v125, v125, v120
	v_lshlrev_b32_e32 v120, 16, v242
	v_and_b32_e32 v121, 0xffff0000, v242
	v_lshlrev_b32_e32 v126, 16, v243
	v_and_b32_e32 v127, 0xffff0000, v243
	v_pk_fma_f32 v[114:115], v[114:115], 0.5, v[126:127] op_sel_hi:[1,0,1]
	v_pk_fma_f32 v[120:121], v[112:113], 0.5, v[120:121] op_sel_hi:[1,0,1]
	v_mul_f32_e32 v113, v115, v115
	v_mul_f32_e32 v112, v121, v121
	v_fmac_f32_e32 v112, v120, v120
	v_fmac_f32_e32 v113, v114, v114
	v_add_f32_e32 v112, v112, v113
	v_add_f32_e32 v112, v125, v112
	v_mov_b32_e32 v113, v112
	s_nop 1
	v_permlane16_swap_b32_e32 v112, v113
	v_cvt_pk_bf16_f32 v116, v116, v117
	v_cvt_pk_bf16_f32 v117, v118, v119
	v_cvt_pk_bf16_f32 v125, v122, v123
	global_store_dwordx2 v[224:225], v[116:117], off offset:256
	s_waitcnt lgkmcnt(0)
	v_add_f32_e32 v112, v112, v113
	v_mov_b32_e32 v113, v112
	s_nop 1
	v_permlane32_swap_b32_e32 v112, v113
	v_cvt_pk_bf16_f32 v116, v120, v121
	v_cvt_pk_bf16_f32 v117, v114, v115
	global_store_dwordx2 v[224:225], v[236:237], off
	global_store_dwordx2 v[224:225], v[124:125], off offset:32
	global_store_dwordx2 v[224:225], v[116:117], off offset:288
	s_and_saveexec_b64 s[34:35], vcc
	s_cbranch_execz .LBB0_1737
	v_lshlrev_b64 v[114:115], 6, v[220:221]
	v_lshl_add_u64 v[114:115], s[16:17], 0, v[114:115]
	v_lshl_add_u64 v[114:115], s[30:31], 2, v[114:115]
	s_lshl_b32 s12, s47, 2
	v_lshl_add_u64 v[114:115], v[114:115], 0, s[12:13]
	s_waitcnt lgkmcnt(0)
	v_add_f32_e32 v112, v112, v113
	global_store_dword v[114:115], v112, off
; #define PG8_GAS __attribute__((address_space(1)))
; __device__ __forceinline__ unsigned pk2_(float lo, float hi) { f32x2c_t v = {lo, hi}; bf16x2c_t b = __builtin_convertvector(v, bf16x2c_t); return __builtin_bit_cast(unsigned, b); }
;     __device__ __forceinline__ void operator()(const f32x4 (&acc)[2][2][4][2], const Unit& u, int wr, int wc, int fr, int fq) const {
;     ...
;         for (int ai = 0; ai < 2; ++ai)
; #pragma unroll
;             for (int m = 0; m < 4; ++m) {
;                 const int r = row0 + ai * HALF + m * 16; const size_t off = (size_t)r * 1024 + col0; float ss = 0.f;
; #pragma unroll
;                 for (int bj = 0; bj < 2; ++bj)
; #pragma unroll
;                     for (int n = 0; n < 2; ++n) {
;                         const u32x2v w0 = bsv[ai][m][bj][n]; f32x4 bs;
;                         bs[0] = __builtin_bit_cast(float, w0.x << 16); bs[1] = __builtin_bit_cast(float, w0.x & 0xffff0000u); bs[2] = __builtin_bit_cast(float, w0.y << 16); bs[3] = __builtin_bit_cast(float, w0.y & 0xffff0000u);
;                         const f32x4 v = bs + acc[ai][bj][m][n] * alpha;
;                         { u32x2v w; w.x = pk2_(v[0], v[1]); w.y = pk2_(v[2], v[3]); *(PG8_GAS u32x2v*)(hb + off + bj * HALF + n * 16) = w; }
;                         ss += (v[0] * v[0] + v[1] * v[1]) + (v[2] * v[2] + v[3] * v[3]);
;                     }
;                 ss += __shfl_xor(ss, 16); ss += __shfl_xor(ss, 32);
;                 if (fq == 0) ((PG8_GAS float*)parts)[(size_t)r * 16 + u.pn * 4 + wc] = ss;
;             }
.LBB0_1737:
	s_or_b64 exec, exec, s[34:35]
	s_waitcnt vmcnt(28)
	v_lshlrev_b32_e32 v112, 16, v222
	s_waitcnt lgkmcnt(0)
	v_and_b32_e32 v113, 0xffff0000, v222
	v_lshlrev_b32_e32 v114, 16, v223
	v_and_b32_e32 v115, 0xffff0000, v223
	v_pk_fma_f32 v[108:109], v[108:109], 0.5, v[112:113] op_sel_hi:[1,0,1]
	v_pk_fma_f32 v[110:111], v[110:111], 0.5, v[114:115] op_sel_hi:[1,0,1]
	v_cvt_pk_bf16_f32 v112, v108, v109
	v_mul_f32_e32 v109, v109, v109
	v_lshl_add_u64 v[114:115], s[14:15], 0, v[218:219]
	v_fmac_f32_e32 v109, v108, v108
	v_mul_f32_e32 v108, v111, v111
	v_cvt_pk_bf16_f32 v113, v110, v111
	v_lshl_add_u64 v[114:115], v[138:139], 1, v[114:115]
	v_fmac_f32_e32 v108, v110, v110
	global_store_dwordx2 v[114:115], v[112:113], off
	v_add_f32_e32 v112, v109, v108
	v_lshlrev_b32_e32 v108, 16, v216
	v_and_b32_e32 v109, 0xffff0000, v216
	v_lshlrev_b32_e32 v110, 16, v217
	v_and_b32_e32 v111, 0xffff0000, v217
	v_pk_fma_f32 v[104:105], v[104:105], 0.5, v[108:109] op_sel_hi:[1,0,1]
	v_pk_fma_f32 v[106:107], v[106:107], 0.5, v[110:111] op_sel_hi:[1,0,1]
	v_cvt_pk_bf16_f32 v108, v104, v105
	v_mul_f32_e32 v105, v105, v105
	v_fmac_f32_e32 v105, v104, v104
	v_mul_f32_e32 v104, v107, v107
	v_fmac_f32_e32 v104, v106, v106
	v_add_f32_e32 v104, v105, v104
	v_add_f32_e32 v109, v112, v104
	v_lshlrev_b32_e32 v104, 16, v214
	v_and_b32_e32 v105, 0xffff0000, v214
	v_lshlrev_b32_e32 v110, 16, v215
	v_and_b32_e32 v111, 0xffff0000, v215
	v_pk_fma_f32 v[102:103], v[102:103], 0.5, v[110:111] op_sel_hi:[1,0,1]
	v_pk_fma_f32 v[100:101], v[100:101], 0.5, v[104:105] op_sel_hi:[1,0,1]
	v_mul_f32_e32 v105, v103, v103
	v_mul_f32_e32 v104, v101, v101
	v_fmac_f32_e32 v104, v100, v100
	v_fmac_f32_e32 v105, v102, v102
	v_add_f32_e32 v104, v104, v105
	v_add_f32_e32 v109, v109, v104
	v_lshlrev_b32_e32 v104, 16, v212
	v_and_b32_e32 v105, 0xffff0000, v212
	v_lshlrev_b32_e32 v110, 16, v213
	v_and_b32_e32 v111, 0xffff0000, v213
	v_pk_fma_f32 v[98:99], v[98:99], 0.5, v[110:111] op_sel_hi:[1,0,1]
	v_pk_fma_f32 v[104:105], v[96:97], 0.5, v[104:105] op_sel_hi:[1,0,1]
	v_mul_f32_e32 v97, v99, v99
	v_mul_f32_e32 v96, v105, v105
	v_fmac_f32_e32 v96, v104, v104
	v_fmac_f32_e32 v97, v98, v98
	v_add_f32_e32 v96, v96, v97
	v_add_f32_e32 v96, v109, v96
	v_mov_b32_e32 v97, v96
	s_nop 1
	v_permlane16_swap_b32_e32 v96, v97
	v_cvt_pk_bf16_f32 v100, v100, v101
	v_cvt_pk_bf16_f32 v101, v102, v103
	v_cvt_pk_bf16_f32 v109, v106, v107
	global_store_dwordx2 v[114:115], v[100:101], off offset:256
	s_waitcnt lgkmcnt(0)
	v_add_f32_e32 v96, v96, v97
	v_mov_b32_e32 v97, v96
	s_nop 1
	v_permlane32_swap_b32_e32 v96, v97
	v_cvt_pk_bf16_f32 v100, v104, v105
	v_cvt_pk_bf16_f32 v101, v98, v99
	global_store_dwordx2 v[114:115], v[108:109], off offset:32
	global_store_dwordx2 v[114:115], v[100:101], off offset:288
	s_and_saveexec_b64 s[34:35], vcc
	s_cbranch_execz .LBB0_1739
	v_lshlrev_b64 v[98:99], 6, v[208:209]
	v_lshl_add_u64 v[98:99], s[16:17], 0, v[98:99]
	v_lshl_add_u64 v[98:99], s[30:31], 2, v[98:99]
	s_lshl_b32 s12, s47, 2
	v_lshl_add_u64 v[98:99], v[98:99], 0, s[12:13]
	s_waitcnt lgkmcnt(0)
	v_add_f32_e32 v96, v96, v97
	global_store_dword v[98:99], v96, off
.LBB0_1739:
	s_or_b64 exec, exec, s[34:35]
	s_waitcnt vmcnt(28)
	v_lshlrev_b32_e32 v96, 16, v210
	s_waitcnt lgkmcnt(0)
	v_and_b32_e32 v97, 0xffff0000, v210
	v_lshlrev_b32_e32 v98, 16, v211
	v_and_b32_e32 v99, 0xffff0000, v211
	v_pk_fma_f32 v[92:93], v[92:93], 0.5, v[96:97] op_sel_hi:[1,0,1]
	v_pk_fma_f32 v[94:95], v[94:95], 0.5, v[98:99] op_sel_hi:[1,0,1]
	v_cvt_pk_bf16_f32 v96, v92, v93
	v_mul_f32_e32 v93, v93, v93
	v_lshl_add_u64 v[98:99], s[14:15], 0, v[206:207]
	v_fmac_f32_e32 v93, v92, v92
	v_mul_f32_e32 v92, v95, v95
	v_cvt_pk_bf16_f32 v97, v94, v95
	v_lshl_add_u64 v[98:99], v[138:139], 1, v[98:99]
	v_fmac_f32_e32 v92, v94, v94
	global_store_dwordx2 v[98:99], v[96:97], off
	v_add_f32_e32 v96, v93, v92
	v_lshlrev_b32_e32 v92, 16, v204
	v_and_b32_e32 v93, 0xffff0000, v204
	v_lshlrev_b32_e32 v94, 16, v205
	v_and_b32_e32 v95, 0xffff0000, v205
	v_pk_fma_f32 v[88:89], v[88:89], 0.5, v[92:93] op_sel_hi:[1,0,1]
	v_pk_fma_f32 v[90:91], v[90:91], 0.5, v[94:95] op_sel_hi:[1,0,1]
	v_cvt_pk_bf16_f32 v92, v88, v89
	v_mul_f32_e32 v89, v89, v89
	v_fmac_f32_e32 v89, v88, v88
	v_mul_f32_e32 v88, v91, v91
	v_fmac_f32_e32 v88, v90, v90
	v_add_f32_e32 v88, v89, v88
	v_add_f32_e32 v93, v96, v88
	v_lshlrev_b32_e32 v88, 16, v202
	v_and_b32_e32 v89, 0xffff0000, v202
	v_lshlrev_b32_e32 v94, 16, v203
	v_and_b32_e32 v95, 0xffff0000, v203
	v_pk_fma_f32 v[86:87], v[86:87], 0.5, v[94:95] op_sel_hi:[1,0,1]
	v_pk_fma_f32 v[84:85], v[84:85], 0.5, v[88:89] op_sel_hi:[1,0,1]
	v_mul_f32_e32 v89, v87, v87
	v_mul_f32_e32 v88, v85, v85
	v_fmac_f32_e32 v88, v84, v84
	v_fmac_f32_e32 v89, v86, v86
	v_add_f32_e32 v88, v88, v89
	v_add_f32_e32 v93, v93, v88
	v_lshlrev_b32_e32 v88, 16, v200
	v_and_b32_e32 v89, 0xffff0000, v200
	v_lshlrev_b32_e32 v94, 16, v201
	v_and_b32_e32 v95, 0xffff0000, v201
	v_pk_fma_f32 v[82:83], v[82:83], 0.5, v[94:95] op_sel_hi:[1,0,1]
	v_pk_fma_f32 v[88:89], v[80:81], 0.5, v[88:89] op_sel_hi:[1,0,1]
	v_mul_f32_e32 v81, v83, v83
	v_mul_f32_e32 v80, v89, v89
	v_fmac_f32_e32 v80, v88, v88
	v_fmac_f32_e32 v81, v82, v82
	v_add_f32_e32 v80, v80, v81
	v_add_f32_e32 v80, v93, v80
	v_mov_b32_e32 v81, v80
	s_nop 1
	v_permlane16_swap_b32_e32 v80, v81
	v_cvt_pk_bf16_f32 v84, v84, v85
	v_cvt_pk_bf16_f32 v85, v86, v87
	v_cvt_pk_bf16_f32 v93, v90, v91
	global_store_dwordx2 v[98:99], v[84:85], off offset:256
	s_waitcnt lgkmcnt(0)
	v_add_f32_e32 v80, v80, v81
	v_mov_b32_e32 v81, v80
	s_nop 1
	v_permlane32_swap_b32_e32 v80, v81
	v_cvt_pk_bf16_f32 v84, v88, v89
	v_cvt_pk_bf16_f32 v85, v82, v83
	global_store_dwordx2 v[98:99], v[92:93], off offset:32
	global_store_dwordx2 v[98:99], v[84:85], off offset:288
	s_and_saveexec_b64 s[34:35], vcc
	s_cbranch_execz .LBB0_1741
	v_lshlrev_b64 v[82:83], 6, v[196:197]
	v_lshl_add_u64 v[82:83], s[16:17], 0, v[82:83]
	v_lshl_add_u64 v[82:83], s[30:31], 2, v[82:83]
	s_lshl_b32 s12, s47, 2
	v_lshl_add_u64 v[82:83], v[82:83], 0, s[12:13]
	s_waitcnt lgkmcnt(0)
	v_add_f32_e32 v80, v80, v81
	global_store_dword v[82:83], v80, off
; #define PG8_GAS __attribute__((address_space(1)))
; __device__ __forceinline__ unsigned pk2_(float lo, float hi) { f32x2c_t v = {lo, hi}; bf16x2c_t b = __builtin_convertvector(v, bf16x2c_t); return __builtin_bit_cast(unsigned, b); }
;     __device__ __forceinline__ void operator()(const f32x4 (&acc)[2][2][4][2], const Unit& u, int wr, int wc, int fr, int fq) const {
;     ...
;         for (int ai = 0; ai < 2; ++ai)
; #pragma unroll
;             for (int m = 0; m < 4; ++m) {
;                 const int r = row0 + ai * HALF + m * 16; const size_t off = (size_t)r * 1024 + col0; float ss = 0.f;
; #pragma unroll
;                 for (int bj = 0; bj < 2; ++bj)
; #pragma unroll
;                     for (int n = 0; n < 2; ++n) {
;                         const u32x2v w0 = bsv[ai][m][bj][n]; f32x4 bs;
;                         bs[0] = __builtin_bit_cast(float, w0.x << 16); bs[1] = __builtin_bit_cast(float, w0.x & 0xffff0000u); bs[2] = __builtin_bit_cast(float, w0.y << 16); bs[3] = __builtin_bit_cast(float, w0.y & 0xffff0000u);
;                         const f32x4 v = bs + acc[ai][bj][m][n] * alpha;
;                         { u32x2v w; w.x = pk2_(v[0], v[1]); w.y = pk2_(v[2], v[3]); *(PG8_GAS u32x2v*)(hb + off + bj * HALF + n * 16) = w; }
;                         ss += (v[0] * v[0] + v[1] * v[1]) + (v[2] * v[2] + v[3] * v[3]);
;                     }
;                 ss += __shfl_xor(ss, 16); ss += __shfl_xor(ss, 32);
;                 if (fq == 0) ((PG8_GAS float*)parts)[(size_t)r * 16 + u.pn * 4 + wc] = ss;
;             }
.LBB0_1741:
	s_or_b64 exec, exec, s[34:35]
	s_waitcnt vmcnt(28)
	v_lshlrev_b32_e32 v80, 16, v198
	s_waitcnt lgkmcnt(0)
	v_and_b32_e32 v81, 0xffff0000, v198
	v_lshlrev_b32_e32 v82, 16, v199
	v_and_b32_e32 v83, 0xffff0000, v199
	v_pk_fma_f32 v[76:77], v[76:77], 0.5, v[80:81] op_sel_hi:[1,0,1]
	v_pk_fma_f32 v[78:79], v[78:79], 0.5, v[82:83] op_sel_hi:[1,0,1]
	v_cvt_pk_bf16_f32 v80, v76, v77
	v_mul_f32_e32 v77, v77, v77
	v_lshl_add_u64 v[82:83], s[14:15], 0, v[194:195]
	v_fmac_f32_e32 v77, v76, v76
	v_mul_f32_e32 v76, v79, v79
	v_cvt_pk_bf16_f32 v81, v78, v79
	v_lshl_add_u64 v[82:83], v[138:139], 1, v[82:83]
	v_fmac_f32_e32 v76, v78, v78
	global_store_dwordx2 v[82:83], v[80:81], off
	v_add_f32_e32 v80, v77, v76
	v_lshlrev_b32_e32 v76, 16, v192
	v_and_b32_e32 v77, 0xffff0000, v192
	v_lshlrev_b32_e32 v78, 16, v193
	v_and_b32_e32 v79, 0xffff0000, v193
	v_pk_fma_f32 v[72:73], v[72:73], 0.5, v[76:77] op_sel_hi:[1,0,1]
	v_pk_fma_f32 v[74:75], v[74:75], 0.5, v[78:79] op_sel_hi:[1,0,1]
	v_cvt_pk_bf16_f32 v76, v72, v73
	v_mul_f32_e32 v73, v73, v73
	v_fmac_f32_e32 v73, v72, v72
	v_mul_f32_e32 v72, v75, v75
	v_fmac_f32_e32 v72, v74, v74
	v_add_f32_e32 v72, v73, v72
	v_add_f32_e32 v77, v80, v72
	v_lshlrev_b32_e32 v72, 16, v190
	v_and_b32_e32 v73, 0xffff0000, v190
	v_lshlrev_b32_e32 v78, 16, v191
	v_and_b32_e32 v79, 0xffff0000, v191
	v_pk_fma_f32 v[70:71], v[70:71], 0.5, v[78:79] op_sel_hi:[1,0,1]
	v_pk_fma_f32 v[68:69], v[68:69], 0.5, v[72:73] op_sel_hi:[1,0,1]
	v_mul_f32_e32 v73, v71, v71
	v_mul_f32_e32 v72, v69, v69
	v_fmac_f32_e32 v72, v68, v68
	v_fmac_f32_e32 v73, v70, v70
	v_add_f32_e32 v72, v72, v73
	v_add_f32_e32 v77, v77, v72
	v_lshlrev_b32_e32 v72, 16, v188
	v_and_b32_e32 v73, 0xffff0000, v188
	v_lshlrev_b32_e32 v78, 16, v189
	v_and_b32_e32 v79, 0xffff0000, v189
	v_pk_fma_f32 v[66:67], v[66:67], 0.5, v[78:79] op_sel_hi:[1,0,1]
	v_pk_fma_f32 v[72:73], v[64:65], 0.5, v[72:73] op_sel_hi:[1,0,1]
	v_mul_f32_e32 v65, v67, v67
	v_mul_f32_e32 v64, v73, v73
	v_fmac_f32_e32 v64, v72, v72
	v_fmac_f32_e32 v65, v66, v66
	v_add_f32_e32 v64, v64, v65
	v_add_f32_e32 v64, v77, v64
	v_mov_b32_e32 v65, v64
	s_nop 1
	v_permlane16_swap_b32_e32 v64, v65
	v_cvt_pk_bf16_f32 v68, v68, v69
	v_cvt_pk_bf16_f32 v69, v70, v71
	v_cvt_pk_bf16_f32 v77, v74, v75
	global_store_dwordx2 v[82:83], v[68:69], off offset:256
	s_waitcnt lgkmcnt(0)
	v_add_f32_e32 v64, v64, v65
	v_mov_b32_e32 v65, v64
	s_nop 1
	v_permlane32_swap_b32_e32 v64, v65
	v_cvt_pk_bf16_f32 v68, v72, v73
	v_cvt_pk_bf16_f32 v69, v66, v67
	global_store_dwordx2 v[82:83], v[76:77], off offset:32
	global_store_dwordx2 v[82:83], v[68:69], off offset:288
	s_and_saveexec_b64 s[34:35], vcc
	s_cbranch_execz .LBB0_1743
	v_lshlrev_b64 v[66:67], 6, v[184:185]
	v_lshl_add_u64 v[66:67], s[16:17], 0, v[66:67]
	v_lshl_add_u64 v[66:67], s[30:31], 2, v[66:67]
	s_lshl_b32 s12, s47, 2
	v_lshl_add_u64 v[66:67], v[66:67], 0, s[12:13]
	s_waitcnt lgkmcnt(0)
	v_add_f32_e32 v64, v64, v65
	global_store_dword v[66:67], v64, off
.LBB0_1743:
	s_or_b64 exec, exec, s[34:35]
	s_waitcnt vmcnt(28)
	v_lshlrev_b32_e32 v64, 16, v186
	s_waitcnt lgkmcnt(0)
	v_and_b32_e32 v65, 0xffff0000, v186
	v_lshlrev_b32_e32 v66, 16, v187
	v_and_b32_e32 v67, 0xffff0000, v187
	v_pk_fma_f32 v[60:61], v[60:61], 0.5, v[64:65] op_sel_hi:[1,0,1]
	v_pk_fma_f32 v[62:63], v[62:63], 0.5, v[66:67] op_sel_hi:[1,0,1]
	v_cvt_pk_bf16_f32 v64, v60, v61
	v_mul_f32_e32 v61, v61, v61
	v_lshl_add_u64 v[66:67], s[14:15], 0, v[182:183]
	v_fmac_f32_e32 v61, v60, v60
	v_mul_f32_e32 v60, v63, v63
	v_cvt_pk_bf16_f32 v65, v62, v63
	v_lshl_add_u64 v[66:67], v[138:139], 1, v[66:67]
	v_fmac_f32_e32 v60, v62, v62
	global_store_dwordx2 v[66:67], v[64:65], off
	v_add_f32_e32 v64, v61, v60
	v_lshlrev_b32_e32 v60, 16, v180
	v_and_b32_e32 v61, 0xffff0000, v180
	v_lshlrev_b32_e32 v62, 16, v181
	v_and_b32_e32 v63, 0xffff0000, v181
	v_pk_fma_f32 v[56:57], v[56:57], 0.5, v[60:61] op_sel_hi:[1,0,1]
	v_pk_fma_f32 v[58:59], v[58:59], 0.5, v[62:63] op_sel_hi:[1,0,1]
	v_cvt_pk_bf16_f32 v60, v56, v57
	v_mul_f32_e32 v57, v57, v57
	v_fmac_f32_e32 v57, v56, v56
	v_mul_f32_e32 v56, v59, v59
	v_fmac_f32_e32 v56, v58, v58
	v_add_f32_e32 v56, v57, v56
	v_add_f32_e32 v61, v64, v56
	v_lshlrev_b32_e32 v56, 16, v178
	v_and_b32_e32 v57, 0xffff0000, v178
	v_lshlrev_b32_e32 v62, 16, v179
	v_and_b32_e32 v63, 0xffff0000, v179
	v_pk_fma_f32 v[54:55], v[54:55], 0.5, v[62:63] op_sel_hi:[1,0,1]
	v_pk_fma_f32 v[52:53], v[52:53], 0.5, v[56:57] op_sel_hi:[1,0,1]
	v_mul_f32_e32 v57, v55, v55
	v_mul_f32_e32 v56, v53, v53
	v_fmac_f32_e32 v56, v52, v52
	v_fmac_f32_e32 v57, v54, v54
	v_add_f32_e32 v56, v56, v57
	v_add_f32_e32 v61, v61, v56
	v_lshlrev_b32_e32 v56, 16, v176
	v_and_b32_e32 v57, 0xffff0000, v176
	v_lshlrev_b32_e32 v62, 16, v177
	v_and_b32_e32 v63, 0xffff0000, v177
	v_pk_fma_f32 v[50:51], v[50:51], 0.5, v[62:63] op_sel_hi:[1,0,1]
	v_pk_fma_f32 v[56:57], v[48:49], 0.5, v[56:57] op_sel_hi:[1,0,1]
	v_mul_f32_e32 v49, v51, v51
	v_mul_f32_e32 v48, v57, v57
	v_fmac_f32_e32 v48, v56, v56
	v_fmac_f32_e32 v49, v50, v50
	v_add_f32_e32 v48, v48, v49
	v_add_f32_e32 v48, v61, v48
	v_mov_b32_e32 v49, v48
	s_nop 1
	v_permlane16_swap_b32_e32 v48, v49
	v_cvt_pk_bf16_f32 v52, v52, v53
	v_cvt_pk_bf16_f32 v53, v54, v55
	v_cvt_pk_bf16_f32 v61, v58, v59
	global_store_dwordx2 v[66:67], v[52:53], off offset:256
	s_waitcnt lgkmcnt(0)
	v_add_f32_e32 v48, v48, v49
	v_mov_b32_e32 v49, v48
	s_nop 1
	v_permlane32_swap_b32_e32 v48, v49
	v_cvt_pk_bf16_f32 v52, v56, v57
	v_cvt_pk_bf16_f32 v53, v50, v51
	global_store_dwordx2 v[66:67], v[60:61], off offset:32
	global_store_dwordx2 v[66:67], v[52:53], off offset:288
	s_and_saveexec_b64 s[34:35], vcc
	s_cbranch_execz .LBB0_1745
	v_lshlrev_b64 v[50:51], 6, v[172:173]
	v_lshl_add_u64 v[50:51], s[16:17], 0, v[50:51]
	v_lshl_add_u64 v[50:51], s[30:31], 2, v[50:51]
	s_lshl_b32 s12, s47, 2
	v_lshl_add_u64 v[50:51], v[50:51], 0, s[12:13]
	s_waitcnt lgkmcnt(0)
	v_add_f32_e32 v48, v48, v49
	global_store_dword v[50:51], v48, off
; #define PG8_GAS __attribute__((address_space(1)))
; __device__ __forceinline__ unsigned pk2_(float lo, float hi) { f32x2c_t v = {lo, hi}; bf16x2c_t b = __builtin_convertvector(v, bf16x2c_t); return __builtin_bit_cast(unsigned, b); }
;     __device__ __forceinline__ void operator()(const f32x4 (&acc)[2][2][4][2], const Unit& u, int wr, int wc, int fr, int fq) const {
;     ...
;         for (int ai = 0; ai < 2; ++ai)
; #pragma unroll
;             for (int m = 0; m < 4; ++m) {
;                 const int r = row0 + ai * HALF + m * 16; const size_t off = (size_t)r * 1024 + col0; float ss = 0.f;
; #pragma unroll
;                 for (int bj = 0; bj < 2; ++bj)
; #pragma unroll
;                     for (int n = 0; n < 2; ++n) {
;                         const u32x2v w0 = bsv[ai][m][bj][n]; f32x4 bs;
;                         bs[0] = __builtin_bit_cast(float, w0.x << 16); bs[1] = __builtin_bit_cast(float, w0.x & 0xffff0000u); bs[2] = __builtin_bit_cast(float, w0.y << 16); bs[3] = __builtin_bit_cast(float, w0.y & 0xffff0000u);
;                         const f32x4 v = bs + acc[ai][bj][m][n] * alpha;
;                         { u32x2v w; w.x = pk2_(v[0], v[1]); w.y = pk2_(v[2], v[3]); *(PG8_GAS u32x2v*)(hb + off + bj * HALF + n * 16) = w; }
;                         ss += (v[0] * v[0] + v[1] * v[1]) + (v[2] * v[2] + v[3] * v[3]);
;                     }
;                 ss += __shfl_xor(ss, 16); ss += __shfl_xor(ss, 32);
;                 if (fq == 0) ((PG8_GAS float*)parts)[(size_t)r * 16 + u.pn * 4 + wc] = ss;
;             }
.LBB0_1745:
	s_or_b64 exec, exec, s[34:35]
	s_waitcnt vmcnt(28)
	v_lshlrev_b32_e32 v48, 16, v174
	s_waitcnt lgkmcnt(0)
	v_and_b32_e32 v49, 0xffff0000, v174
	v_lshlrev_b32_e32 v50, 16, v175
	v_and_b32_e32 v51, 0xffff0000, v175
	v_pk_fma_f32 v[44:45], v[44:45], 0.5, v[48:49] op_sel_hi:[1,0,1]
	v_pk_fma_f32 v[46:47], v[46:47], 0.5, v[50:51] op_sel_hi:[1,0,1]
	v_cvt_pk_bf16_f32 v48, v44, v45
	v_mul_f32_e32 v45, v45, v45
	v_lshl_add_u64 v[50:51], s[14:15], 0, v[170:171]
	v_fmac_f32_e32 v45, v44, v44
	v_mul_f32_e32 v44, v47, v47
	v_cvt_pk_bf16_f32 v49, v46, v47
	v_lshl_add_u64 v[50:51], v[138:139], 1, v[50:51]
	v_fmac_f32_e32 v44, v46, v46
	global_store_dwordx2 v[50:51], v[48:49], off
	v_add_f32_e32 v48, v45, v44
	v_lshlrev_b32_e32 v44, 16, v168
	v_and_b32_e32 v45, 0xffff0000, v168
	v_lshlrev_b32_e32 v46, 16, v169
	v_and_b32_e32 v47, 0xffff0000, v169
	v_pk_fma_f32 v[40:41], v[40:41], 0.5, v[44:45] op_sel_hi:[1,0,1]
	v_pk_fma_f32 v[42:43], v[42:43], 0.5, v[46:47] op_sel_hi:[1,0,1]
	v_cvt_pk_bf16_f32 v44, v40, v41
	v_mul_f32_e32 v41, v41, v41
	v_fmac_f32_e32 v41, v40, v40
	v_mul_f32_e32 v40, v43, v43
	v_fmac_f32_e32 v40, v42, v42
	v_add_f32_e32 v40, v41, v40
	v_add_f32_e32 v45, v48, v40
	v_lshlrev_b32_e32 v40, 16, v166
	v_and_b32_e32 v41, 0xffff0000, v166
	v_lshlrev_b32_e32 v46, 16, v167
	v_and_b32_e32 v47, 0xffff0000, v167
	v_pk_fma_f32 v[38:39], v[38:39], 0.5, v[46:47] op_sel_hi:[1,0,1]
	v_pk_fma_f32 v[36:37], v[36:37], 0.5, v[40:41] op_sel_hi:[1,0,1]
	v_mul_f32_e32 v41, v39, v39
	v_mul_f32_e32 v40, v37, v37
	v_fmac_f32_e32 v40, v36, v36
	v_fmac_f32_e32 v41, v38, v38
	v_add_f32_e32 v40, v40, v41
	v_add_f32_e32 v45, v45, v40
	v_lshlrev_b32_e32 v40, 16, v164
	v_and_b32_e32 v41, 0xffff0000, v164
	v_lshlrev_b32_e32 v46, 16, v165
	v_and_b32_e32 v47, 0xffff0000, v165
	v_pk_fma_f32 v[34:35], v[34:35], 0.5, v[46:47] op_sel_hi:[1,0,1]
	v_pk_fma_f32 v[40:41], v[32:33], 0.5, v[40:41] op_sel_hi:[1,0,1]
	v_mul_f32_e32 v33, v35, v35
	v_mul_f32_e32 v32, v41, v41
	v_fmac_f32_e32 v32, v40, v40
	v_fmac_f32_e32 v33, v34, v34
	v_add_f32_e32 v32, v32, v33
	v_add_f32_e32 v32, v45, v32
	v_mov_b32_e32 v33, v32
	s_nop 1
	v_permlane16_swap_b32_e32 v32, v33
	v_cvt_pk_bf16_f32 v36, v36, v37
	v_cvt_pk_bf16_f32 v37, v38, v39
	v_cvt_pk_bf16_f32 v45, v42, v43
	global_store_dwordx2 v[50:51], v[36:37], off offset:256
	s_waitcnt lgkmcnt(0)
	v_add_f32_e32 v32, v32, v33
	v_mov_b32_e32 v33, v32
	s_nop 1
	v_permlane32_swap_b32_e32 v32, v33
	v_cvt_pk_bf16_f32 v36, v40, v41
	v_cvt_pk_bf16_f32 v37, v34, v35
	global_store_dwordx2 v[50:51], v[44:45], off offset:32
	global_store_dwordx2 v[50:51], v[36:37], off offset:288
	s_and_saveexec_b64 s[34:35], vcc
	s_cbranch_execz .LBB0_1747
	v_lshlrev_b64 v[34:35], 6, v[160:161]
	v_lshl_add_u64 v[34:35], s[16:17], 0, v[34:35]
	v_lshl_add_u64 v[34:35], s[30:31], 2, v[34:35]
	s_lshl_b32 s12, s47, 2
	v_lshl_add_u64 v[34:35], v[34:35], 0, s[12:13]
	s_waitcnt lgkmcnt(0)
	v_add_f32_e32 v32, v32, v33
	global_store_dword v[34:35], v32, off
; #define PG8_GAS __attribute__((address_space(1)))
; __device__ __forceinline__ unsigned pk2_(float lo, float hi) { f32x2c_t v = {lo, hi}; bf16x2c_t b = __builtin_convertvector(v, bf16x2c_t); return __builtin_bit_cast(unsigned, b); }
;     __device__ __forceinline__ void operator()(const f32x4 (&acc)[2][2][4][2], const Unit& u, int wr, int wc, int fr, int fq) const {
;     ...
;         for (int ai = 0; ai < 2; ++ai)
; #pragma unroll
;             for (int m = 0; m < 4; ++m) {
;                 const int r = row0 + ai * HALF + m * 16; const size_t off = (size_t)r * 1024 + col0; float ss = 0.f;
; #pragma unroll
;                 for (int bj = 0; bj < 2; ++bj)
; #pragma unroll
;                     for (int n = 0; n < 2; ++n) {
;                         const u32x2v w0 = bsv[ai][m][bj][n]; f32x4 bs;
;                         bs[0] = __builtin_bit_cast(float, w0.x << 16); bs[1] = __builtin_bit_cast(float, w0.x & 0xffff0000u); bs[2] = __builtin_bit_cast(float, w0.y << 16); bs[3] = __builtin_bit_cast(float, w0.y & 0xffff0000u);
;                         const f32x4 v = bs + acc[ai][bj][m][n] * alpha;
;                         { u32x2v w; w.x = pk2_(v[0], v[1]); w.y = pk2_(v[2], v[3]); *(PG8_GAS u32x2v*)(hb + off + bj * HALF + n * 16) = w; }
;                         ss += (v[0] * v[0] + v[1] * v[1]) + (v[2] * v[2] + v[3] * v[3]);
;                     }
;                 ss += __shfl_xor(ss, 16); ss += __shfl_xor(ss, 32);
;                 if (fq == 0) ((PG8_GAS float*)parts)[(size_t)r * 16 + u.pn * 4 + wc] = ss;
;             }
.LBB0_1747:
	s_or_b64 exec, exec, s[34:35]
	s_waitcnt vmcnt(28)
	v_lshlrev_b32_e32 v32, 16, v162
	s_waitcnt lgkmcnt(0)
	v_and_b32_e32 v33, 0xffff0000, v162
	v_lshlrev_b32_e32 v34, 16, v163
	v_and_b32_e32 v35, 0xffff0000, v163
	v_pk_fma_f32 v[28:29], v[28:29], 0.5, v[32:33] op_sel_hi:[1,0,1]
	v_pk_fma_f32 v[30:31], v[30:31], 0.5, v[34:35] op_sel_hi:[1,0,1]
	v_cvt_pk_bf16_f32 v32, v28, v29
	v_mul_f32_e32 v29, v29, v29
	v_lshl_add_u64 v[34:35], s[14:15], 0, v[158:159]
	v_fmac_f32_e32 v29, v28, v28
	v_mul_f32_e32 v28, v31, v31
	v_cvt_pk_bf16_f32 v33, v30, v31
	v_lshl_add_u64 v[34:35], v[138:139], 1, v[34:35]
	v_fmac_f32_e32 v28, v30, v30
	global_store_dwordx2 v[34:35], v[32:33], off
	v_add_f32_e32 v32, v29, v28
	v_lshlrev_b32_e32 v28, 16, v156
	v_and_b32_e32 v29, 0xffff0000, v156
	v_lshlrev_b32_e32 v30, 16, v157
	v_and_b32_e32 v31, 0xffff0000, v157
	v_pk_fma_f32 v[24:25], v[24:25], 0.5, v[28:29] op_sel_hi:[1,0,1]
	v_pk_fma_f32 v[26:27], v[26:27], 0.5, v[30:31] op_sel_hi:[1,0,1]
	v_cvt_pk_bf16_f32 v28, v24, v25
	v_mul_f32_e32 v25, v25, v25
	v_fmac_f32_e32 v25, v24, v24
	v_mul_f32_e32 v24, v27, v27
	v_fmac_f32_e32 v24, v26, v26
	v_add_f32_e32 v24, v25, v24
	v_add_f32_e32 v29, v32, v24
	v_lshlrev_b32_e32 v24, 16, v154
	v_and_b32_e32 v25, 0xffff0000, v154
	v_lshlrev_b32_e32 v30, 16, v155
	v_and_b32_e32 v31, 0xffff0000, v155
	v_pk_fma_f32 v[22:23], v[22:23], 0.5, v[30:31] op_sel_hi:[1,0,1]
	v_pk_fma_f32 v[20:21], v[20:21], 0.5, v[24:25] op_sel_hi:[1,0,1]
	v_mul_f32_e32 v25, v23, v23
	v_mul_f32_e32 v24, v21, v21
	v_fmac_f32_e32 v24, v20, v20
	v_fmac_f32_e32 v25, v22, v22
	v_add_f32_e32 v24, v24, v25
	v_add_f32_e32 v29, v29, v24
	v_lshlrev_b32_e32 v24, 16, v152
	v_and_b32_e32 v25, 0xffff0000, v152
	v_lshlrev_b32_e32 v30, 16, v153
	v_and_b32_e32 v31, 0xffff0000, v153
	v_pk_fma_f32 v[18:19], v[18:19], 0.5, v[30:31] op_sel_hi:[1,0,1]
	v_pk_fma_f32 v[24:25], v[16:17], 0.5, v[24:25] op_sel_hi:[1,0,1]
	v_mul_f32_e32 v17, v19, v19
	v_mul_f32_e32 v16, v25, v25
	v_fmac_f32_e32 v16, v24, v24
	v_fmac_f32_e32 v17, v18, v18
	v_add_f32_e32 v16, v16, v17
	v_add_f32_e32 v16, v29, v16
	v_mov_b32_e32 v17, v16
	s_nop 1
	v_permlane16_swap_b32_e32 v16, v17
	v_cvt_pk_bf16_f32 v20, v20, v21
	v_cvt_pk_bf16_f32 v21, v22, v23
	v_cvt_pk_bf16_f32 v29, v26, v27
	global_store_dwordx2 v[34:35], v[20:21], off offset:256
	s_waitcnt lgkmcnt(0)
	v_add_f32_e32 v16, v16, v17
	v_mov_b32_e32 v17, v16
	s_nop 1
	v_permlane32_swap_b32_e32 v16, v17
	v_cvt_pk_bf16_f32 v20, v24, v25
	v_cvt_pk_bf16_f32 v21, v18, v19
	global_store_dwordx2 v[34:35], v[28:29], off offset:32
	global_store_dwordx2 v[34:35], v[20:21], off offset:288
	s_and_saveexec_b64 s[34:35], vcc
	s_cbranch_execz .LBB0_1749
	v_lshlrev_b64 v[18:19], 6, v[148:149]
	v_lshl_add_u64 v[18:19], s[16:17], 0, v[18:19]
	v_lshl_add_u64 v[18:19], s[30:31], 2, v[18:19]
	s_lshl_b32 s12, s47, 2
	v_lshl_add_u64 v[18:19], v[18:19], 0, s[12:13]
	s_waitcnt lgkmcnt(0)
	v_add_f32_e32 v16, v16, v17
	global_store_dword v[18:19], v16, off
.LBB0_1749:
	s_or_b64 exec, exec, s[34:35]
	s_waitcnt vmcnt(28)
	v_lshlrev_b32_e32 v16, 16, v150
	s_waitcnt lgkmcnt(0)
	v_and_b32_e32 v17, 0xffff0000, v150
	v_lshlrev_b32_e32 v18, 16, v151
	v_and_b32_e32 v19, 0xffff0000, v151
	v_pk_fma_f32 v[12:13], v[12:13], 0.5, v[16:17] op_sel_hi:[1,0,1]
	v_pk_fma_f32 v[14:15], v[14:15], 0.5, v[18:19] op_sel_hi:[1,0,1]
	v_cvt_pk_bf16_f32 v16, v12, v13
	v_mul_f32_e32 v13, v13, v13
	v_lshl_add_u64 v[18:19], s[14:15], 0, v[146:147]
	v_fmac_f32_e32 v13, v12, v12
	v_mul_f32_e32 v12, v15, v15
	v_cvt_pk_bf16_f32 v17, v14, v15
	v_lshl_add_u64 v[18:19], v[138:139], 1, v[18:19]
	v_fmac_f32_e32 v12, v14, v14
	global_store_dwordx2 v[18:19], v[16:17], off
	v_add_f32_e32 v16, v13, v12
	v_lshlrev_b32_e32 v12, 16, v144
	v_and_b32_e32 v13, 0xffff0000, v144
	v_lshlrev_b32_e32 v14, 16, v145
	v_and_b32_e32 v15, 0xffff0000, v145
	v_pk_fma_f32 v[8:9], v[8:9], 0.5, v[12:13] op_sel_hi:[1,0,1]
	v_pk_fma_f32 v[10:11], v[10:11], 0.5, v[14:15] op_sel_hi:[1,0,1]
	v_cvt_pk_bf16_f32 v12, v8, v9
	v_mul_f32_e32 v9, v9, v9
	v_fmac_f32_e32 v9, v8, v8
	v_mul_f32_e32 v8, v11, v11
	v_fmac_f32_e32 v8, v10, v10
	v_add_f32_e32 v8, v9, v8
	v_add_f32_e32 v13, v16, v8
	v_lshlrev_b32_e32 v8, 16, v142
	v_and_b32_e32 v9, 0xffff0000, v142
	v_lshlrev_b32_e32 v14, 16, v143
	v_and_b32_e32 v15, 0xffff0000, v143
	v_pk_fma_f32 v[6:7], v[6:7], 0.5, v[14:15] op_sel_hi:[1,0,1]
	v_pk_fma_f32 v[4:5], v[4:5], 0.5, v[8:9] op_sel_hi:[1,0,1]
	v_mul_f32_e32 v9, v7, v7
	v_mul_f32_e32 v8, v5, v5
	v_fmac_f32_e32 v8, v4, v4
	v_fmac_f32_e32 v9, v6, v6
	v_add_f32_e32 v8, v8, v9
	v_add_f32_e32 v13, v13, v8
	v_lshlrev_b32_e32 v8, 16, v140
	v_and_b32_e32 v9, 0xffff0000, v140
	v_lshlrev_b32_e32 v14, 16, v141
	v_and_b32_e32 v15, 0xffff0000, v141
	v_pk_fma_f32 v[2:3], v[2:3], 0.5, v[14:15] op_sel_hi:[1,0,1]
	v_pk_fma_f32 v[8:9], v[0:1], 0.5, v[8:9] op_sel_hi:[1,0,1]
	v_mul_f32_e32 v1, v3, v3
	v_mul_f32_e32 v0, v9, v9
	v_fmac_f32_e32 v0, v8, v8
	v_fmac_f32_e32 v1, v2, v2
	v_add_f32_e32 v0, v0, v1
	v_add_f32_e32 v0, v13, v0
	v_mov_b32_e32 v1, v0
	s_nop 1
	v_permlane16_swap_b32_e32 v0, v1
	v_cvt_pk_bf16_f32 v4, v4, v5
	v_cvt_pk_bf16_f32 v5, v6, v7
	v_cvt_pk_bf16_f32 v13, v10, v11
	global_store_dwordx2 v[18:19], v[4:5], off offset:256
	s_waitcnt lgkmcnt(0)
	v_add_f32_e32 v0, v0, v1
	v_mov_b32_e32 v1, v0
	s_nop 1
	v_permlane32_swap_b32_e32 v0, v1
	v_cvt_pk_bf16_f32 v4, v8, v9
	v_cvt_pk_bf16_f32 v5, v2, v3
	global_store_dwordx2 v[18:19], v[12:13], off offset:32
	global_store_dwordx2 v[18:19], v[4:5], off offset:288
	s_and_saveexec_b64 s[34:35], vcc
	s_cbranch_execz .LBB0_1751
	v_lshlrev_b64 v[2:3], 6, v[136:137]
	v_lshl_add_u64 v[2:3], s[16:17], 0, v[2:3]
	v_lshl_add_u64 v[2:3], s[30:31], 2, v[2:3]
	s_lshl_b32 s12, s47, 2
	v_lshl_add_u64 v[2:3], v[2:3], 0, s[12:13]
	s_waitcnt lgkmcnt(0)
	v_add_f32_e32 v0, v0, v1
	global_store_dword v[2:3], v0, off
